# SwiGLU epilogue compute hand-rewritten: in-place packed f32 per row, 8 independent elements per stage, same op order/rounding; plus InProj rstd LDS cache
# speedup vs baseline: 1.0630x; 1.0102x over previous
.LBB0_87:
	s_add_u32 s26, s22, 0x6b00000
	s_addc_u32 s27, s23, 0
	s_lshl_b32 s30, s30, 5
	s_and_b32 s41, s30, 0x60
	s_add_i32 m0, s15, 0x18000
	v_lshl_add_u64 v[10:11], v[10:11], 0, s[16:17]
	s_lshl_b32 s34, s72, 5
	s_lshl_b32 s40, s29, 13
	s_lshl_b32 s42, s41, 7
	s_waitcnt vmcnt(2)
	s_barrier
	global_load_lds_dwordx4 v[10:11], off
	v_lshl_add_u64 v[8:9], v[8:9], 0, s[16:17]
	s_add_i32 m0, s15, 0x1a000
	s_add_i32 s61, s15, 0x8000
	s_add_i32 s62, s15, 0xa000
	global_load_lds_dwordx4 v[8:9], off
	v_lshl_add_u64 v[4:5], v[4:5], 0, s[16:17]
	s_mov_b32 m0, s61
	s_add_u32 s30, s18, 0x40080
	global_load_lds_dwordx4 v[4:5], off
	v_lshl_add_u64 v[4:5], v[6:7], 0, s[16:17]
	s_mov_b32 m0, s62
	s_addc_u32 s31, s19, 0
	global_load_lds_dwordx4 v[4:5], off
	s_add_i32 m0, s15, 0x1c000
	v_lshl_add_u64 v[4:5], s[30:31], 0, v[2:3]
	global_load_lds_dwordx4 v[4:5], off
	v_lshl_add_u64 v[4:5], s[30:31], 0, v[176:177]
	s_add_i32 m0, s15, 0x1e000
	s_cmpk_lt_u32 s28, 0x100
	global_load_lds_dwordx4 v[4:5], off
	v_lshrrev_b32_e32 v4, 1, v12
	v_and_b32_e32 v4, 24, v4
	v_and_b32_e32 v5, 15, v12
	v_lshlrev_b32_e32 v6, 1, v4
	v_lshl_or_b32 v1, s29, 6, v5
	v_lshl_or_b32 v5, v5, 6, v6
	v_lshlrev_b32_e32 v6, 2, v12
	v_and_b32_e32 v6, 32, v6
	v_bitop3_b32 v7, v5, s40, v6 bitop3:0xde
	v_bitop3_b32 v233, v5, s42, v6 bitop3:0xde
	v_lshlrev_b32_e32 v5, 14, v17
	v_and_b32_e32 v5, 0xffff8000, v5
	v_lshl_add_u32 v5, v16, 11, v5
	v_and_b32_e32 v6, 1, v17
	v_lshl_or_b32 v5, v6, 6, v5
	v_lshl_add_u32 v182, v18, 1, v5
	v_lshlrev_b32_e32 v5, 14, v13
	v_and_b32_e32 v5, 0xffff8000, v5
	s_waitcnt vmcnt(6)
	v_lshl_add_u32 v5, v14, 11, v5
	v_and_b32_e32 v6, 1, v13
	v_or_b32_e32 v234, s41, v4
	v_lshl_or_b32 v5, v6, 6, v5
	v_readlane_b32 s40, v254, 30
	s_cselect_b64 s[28:29], -1, 0
	v_mov_b32_e32 v183, v3
	v_lshl_add_u32 v184, v15, 1, v5
	v_mov_b32_e32 v185, v3
	s_mov_b32 s63, 0
	s_mov_b32 s73, -1
	v_add_u32_e32 v235, 0, v7
	s_lshl_b64 s[30:31], s[34:35], 2
	v_lshlrev_b32_e32 v236, 2, v4
	v_readlane_b32 s34, v254, 18
	s_mov_b32 s44, s40
	s_barrier
	v_readlane_b32 s41, v254, 31
	s_branch .LBB0_90

.LBB0_98:
	v_lshl_add_u32 v210, s44, 8, v1
	v_ashrrev_i32_e32 v211, 31, v210
	s_mov_b32 s74, s44
	v_lshlrev_b32_e32 v250, 2, v0
	v_add_u32_e32 v250, 0x20000, v250
	s_cmp_eq_u32 s74, s73
	s_cbranch_scc1 .Lip_cached
	v_lshl_add_u64 v[44:45], v[210:211], 4, s[6:7]
	global_load_dwordx4 v[44:47], v[44:45], off
	s_mov_b32 s4, 0xf800000
	v_or_b32_e32 v208, 16, v210
	v_ashrrev_i32_e32 v209, 31, v208
	v_or_b32_e32 v206, 32, v210
	v_ashrrev_i32_e32 v207, 31, v206
	v_or_b32_e32 v204, 48, v210
	v_ashrrev_i32_e32 v205, 31, v204
	v_add_u32_e32 v202, 0x80, v210
	v_ashrrev_i32_e32 v203, 31, v202
	v_add_u32_e32 v200, 0x90, v210
	v_ashrrev_i32_e32 v201, 31, v200
	v_add_u32_e32 v198, 0xa0, v210
	v_ashrrev_i32_e32 v199, 31, v198
	v_add_u32_e32 v194, 0xb0, v210
	v_ashrrev_i32_e32 v195, 31, v194
	s_cmp_gt_i32 s34, 1
	s_cselect_b64 s[18:19], -1, 0
	v_cndmask_b32_e64 v160, 0, 1, s[42:43]
	v_cmp_ne_u32_e64 s[42:43], 1, v160
	s_waitcnt vmcnt(0)
	v_mov_b32_e32 v64, v45
	v_mov_b32_e32 v65, v46
	v_mov_b32_e32 v45, v47
	v_pk_add_f32 v[44:45], v[64:65], v[44:45]
	s_nop 0
	v_add_f32_e32 v44, v44, v45
	v_fmamk_f32 v44, v44, 0x3a800000, v215
	v_cmp_gt_f32_e32 vcc, s4, v44
	v_mul_f32_e32 v45, 0x4f800000, v44
	s_nop 0
	v_cndmask_b32_e32 v44, v44, v45, vcc
	v_sqrt_f32_e32 v45, v44
	s_nop 0
	v_add_u32_e32 v46, -1, v45
	v_fma_f32 v47, -v46, v45, v44
	v_cmp_ge_f32_e64 s[4:5], 0, v47
	v_add_u32_e32 v47, 1, v45
	s_nop 0
	v_cndmask_b32_e64 v46, v45, v46, s[4:5]
	v_fma_f32 v45, -v47, v45, v44
	v_cmp_lt_f32_e64 s[4:5], 0, v45
	s_nop 1
	v_cndmask_b32_e64 v45, v46, v47, s[4:5]
	v_mul_f32_e32 v46, 0x37800000, v45
	v_cndmask_b32_e32 v45, v45, v46, vcc
	v_cmp_class_f32_e32 vcc, v44, v216
	s_nop 1
	v_cndmask_b32_e32 v44, v45, v44, vcc
	v_div_scale_f32 v45, s[4:5], v44, v44, 1.0
	v_rcp_f32_e32 v46, v45
	s_mov_b64 s[4:5], -1
	v_fma_f32 v47, -v45, v46, 1.0
	v_fmac_f32_e32 v46, v47, v46
	v_div_scale_f32 v47, vcc, 1.0, v44, 1.0
	v_mul_f32_e32 v64, v47, v46
	v_fma_f32 v65, -v45, v64, v47
	v_fmac_f32_e32 v64, v65, v46
	v_fma_f32 v45, -v45, v64, v47
	v_div_fmas_f32 v45, v45, v46, v64
	v_div_fixup_f32 v212, v45, v44, 1.0
	ds_write_b32 v250, v212
	v_lshl_add_u64 v[44:45], v[208:209], 4, s[6:7]
	global_load_dwordx4 v[156:159], v[44:45], off
	v_lshl_add_u64 v[44:45], v[206:207], 4, s[6:7]
	global_load_dwordx4 v[136:139], v[44:45], off
	v_lshl_add_u64 v[44:45], v[204:205], 4, s[6:7]
	global_load_dwordx4 v[116:119], v[44:45], off
	v_lshl_add_u64 v[44:45], v[202:203], 4, s[6:7]
	global_load_dwordx4 v[96:99], v[44:45], off
	v_lshl_add_u64 v[44:45], v[200:201], 4, s[6:7]
	global_load_dwordx4 v[76:79], v[44:45], off
	v_lshl_add_u64 v[44:45], v[198:199], 4, s[6:7]
	global_load_dwordx4 v[64:67], v[44:45], off
	v_lshl_add_u64 v[44:45], v[194:195], 4, s[6:7]
	global_load_dwordx4 v[44:47], v[44:45], off
	s_branch .Lip_join
.Lip_cached:
	ds_read_b32 v212, v250
	ds_read_b32 v156, v250 offset:2048
	ds_read_b32 v136, v250 offset:4096
	ds_read_b32 v116, v250 offset:6144
	ds_read_b32 v96, v250 offset:8192
	ds_read_b32 v76, v250 offset:10240
	ds_read_b32 v64, v250 offset:12288
	ds_read_b32 v44, v250 offset:14336
	v_or_b32_e32 v208, 16, v210
	v_or_b32_e32 v206, 32, v210
	v_or_b32_e32 v204, 48, v210
	v_add_u32_e32 v202, 0x80, v210
	v_add_u32_e32 v200, 0x90, v210
	v_add_u32_e32 v198, 0xa0, v210
	v_add_u32_e32 v194, 0xb0, v210
	s_cmp_gt_i32 s34, 1
	s_cselect_b64 s[18:19], -1, 0
	v_cndmask_b32_e64 v160, 0, 1, s[42:43]
	s_nop 0
	v_cmp_ne_u32_e64 s[42:43], 1, v160
	s_mov_b64 s[4:5], -1
	s_waitcnt lgkmcnt(0)
.Lip_join:
	v_pk_mul_f32 v[154:155], v[154:155], v[212:213] op_sel_hi:[1,0]
	v_pk_mul_f32 v[152:153], v[152:153], v[212:213] op_sel_hi:[1,0]
	v_pk_mul_f32 v[150:151], v[150:151], v[212:213] op_sel_hi:[1,0]
	v_pk_mul_f32 v[148:149], v[148:149], v[212:213] op_sel_hi:[1,0]
	s_and_b64 vcc, exec, s[18:19]
	s_cbranch_vccz .LBB0_102
	v_mov_b64_e32 v[166:167], v[150:151]
	v_mov_b64_e32 v[162:163], v[154:155]
	s_and_b64 vcc, exec, s[42:43]
	v_mov_b64_e32 v[164:165], v[148:149]
	v_mov_b64_e32 v[160:161], v[152:153]
	s_cbranch_vccnz .LBB0_101
	v_pk_mul_f32 v[160:161], v[154:155], v[154:155]
	v_pk_mul_f32 v[162:163], v[152:153], v[152:153]
	s_mov_b32 s4, 0xf800000
	v_pk_mov_b32 v[164:165], v[162:163], v[160:161] op_sel:[1,0]
	v_mov_b32_e32 v163, v161
	v_pk_add_f32 v[160:161], v[164:165], v[162:163]
	v_pk_mul_f32 v[162:163], v[150:151], v[150:151]
	v_pk_mul_f32 v[164:165], v[148:149], v[148:149]
	v_mov_b32_e32 v166, v162
	v_mov_b32_e32 v167, v164
	v_mov_b32_e32 v164, v163
	v_pk_add_f32 v[162:163], v[166:167], v[164:165]
	v_add_f32_e32 v160, v160, v161
	v_add_f32_e32 v160, v163, v160
	v_add_f32_e32 v160, v162, v160
	v_and_b32_e32 v162, 64, v218
	v_xor_b32_e32 v161, 16, v218
	v_add_u32_e32 v162, 64, v162
	v_cmp_lt_i32_e32 vcc, v161, v162
	s_nop 1
	v_cndmask_b32_e32 v161, v218, v161, vcc
	v_lshlrev_b32_e32 v161, 2, v161
	ds_bpermute_b32 v161, v161, v160
	s_waitcnt lgkmcnt(0)
	v_add_f32_e32 v160, v160, v161
	v_xor_b32_e32 v161, 32, v218
	v_cmp_lt_i32_e32 vcc, v161, v162
	s_nop 1
	v_cndmask_b32_e32 v161, v218, v161, vcc
	v_lshlrev_b32_e32 v161, 2, v161
	ds_bpermute_b32 v161, v161, v160
	s_waitcnt lgkmcnt(0)
	v_add_f32_e32 v160, v160, v161
	v_fmamk_f32 v160, v160, 0x3d000000, v215
	v_mul_f32_e32 v161, 0x4f800000, v160
	v_cmp_gt_f32_e32 vcc, s4, v160
	s_nop 1
	v_cndmask_b32_e32 v160, v160, v161, vcc
	v_sqrt_f32_e32 v161, v160
	s_nop 0
	v_add_u32_e32 v162, -1, v161
	v_fma_f32 v163, -v162, v161, v160
	v_cmp_ge_f32_e64 s[4:5], 0, v163
	v_add_u32_e32 v163, 1, v161
	s_nop 0
	v_cndmask_b32_e64 v162, v161, v162, s[4:5]
	v_fma_f32 v161, -v163, v161, v160
	v_cmp_lt_f32_e64 s[4:5], 0, v161
	s_nop 1
	v_cndmask_b32_e64 v161, v162, v163, s[4:5]
	v_mul_f32_e32 v162, 0x37800000, v161
	v_cndmask_b32_e32 v161, v161, v162, vcc
	v_cmp_class_f32_e32 vcc, v160, v216
	s_nop 1
	v_cndmask_b32_e32 v160, v161, v160, vcc
	v_div_scale_f32 v161, s[4:5], v160, v160, 1.0
	v_rcp_f32_e32 v162, v161
	s_nop 0
	v_fma_f32 v163, -v161, v162, 1.0
	v_fmac_f32_e32 v162, v163, v162
	v_div_scale_f32 v163, vcc, 1.0, v160, 1.0
	v_mul_f32_e32 v164, v163, v162
	v_fma_f32 v165, -v161, v164, v163
	v_fmac_f32_e32 v164, v165, v162
	v_fma_f32 v161, -v161, v164, v163
	v_div_fmas_f32 v161, v161, v162, v164
	v_div_fixup_f32 v164, v161, v160, 1.0
	v_pk_mul_f32 v[160:161], v[152:153], v[164:165] op_sel_hi:[1,0]
	v_pk_mul_f32 v[162:163], v[154:155], v[164:165] op_sel_hi:[1,0]
	v_pk_mul_f32 v[196:197], v[148:149], v[164:165] op_sel_hi:[1,0]
	v_pk_mul_f32 v[164:165], v[150:151], v[164:165] op_sel_hi:[1,0]
	v_pk_mul_f32 v[162:163], v[192:193], v[162:163]
	v_pk_mul_f32 v[160:161], v[190:191], v[160:161]
	v_pk_mul_f32 v[166:167], v[188:189], v[164:165]
	v_pk_mul_f32 v[164:165], v[186:187], v[196:197]

.LBB0_110:
	s_cmp_eq_u32 s74, s73
	s_cbranch_scc1 .Lip_c1
	s_waitcnt vmcnt(7)
	v_add_f32_e32 v140, v156, v157
	v_add_f32_e32 v141, v158, v159
	v_add_f32_e32 v140, v140, v141
	v_fmamk_f32 v140, v140, 0x3a800000, v215
	s_mov_b32 s4, 0xf800000
	v_mul_f32_e32 v141, 0x4f800000, v140
	v_cmp_gt_f32_e32 vcc, s4, v140
	s_nop 1
	v_cndmask_b32_e32 v140, v140, v141, vcc
	v_sqrt_f32_e32 v141, v140
	s_nop 0
	v_add_u32_e32 v142, -1, v141
	v_fma_f32 v143, -v142, v141, v140
	v_cmp_ge_f32_e64 s[4:5], 0, v143
	v_add_u32_e32 v143, 1, v141
	s_nop 0
	v_cndmask_b32_e64 v142, v141, v142, s[4:5]
	v_fma_f32 v141, -v143, v141, v140
	v_cmp_lt_f32_e64 s[4:5], 0, v141
	s_nop 1
	v_cndmask_b32_e64 v141, v142, v143, s[4:5]
	v_mul_f32_e32 v142, 0x37800000, v141
	v_cndmask_b32_e32 v141, v141, v142, vcc
	v_cmp_class_f32_e32 vcc, v140, v216
	s_nop 1
	v_cndmask_b32_e32 v140, v141, v140, vcc
	v_div_scale_f32 v141, s[4:5], v140, v140, 1.0
	v_rcp_f32_e32 v142, v141
	s_mov_b64 s[4:5], -1
	v_fma_f32 v143, -v141, v142, 1.0
	v_fmac_f32_e32 v142, v143, v142
	v_div_scale_f32 v143, vcc, 1.0, v140, 1.0
	v_mul_f32_e32 v144, v143, v142
	v_fma_f32 v145, -v141, v144, v143
	v_fmac_f32_e32 v144, v145, v142
	v_fma_f32 v141, -v141, v144, v143
	v_div_fmas_f32 v141, v141, v142, v144
	v_div_fixup_f32 v156, v141, v140, 1.0
	ds_write_b32 v250, v156 offset:2048
	s_branch .Lip_j1
.Lip_c1:
	s_mov_b64 s[4:5], -1
.Lip_j1:
	v_cvt_pk_bf16_f32 v140, v148, v149
	v_cvt_pk_bf16_f32 v141, v150, v151
	v_cvt_pk_bf16_f32 v142, v152, v153
	v_cvt_pk_bf16_f32 v143, v154, v155
	v_pk_mul_f32 v[134:135], v[134:135], v[156:157] op_sel_hi:[1,0]
	v_pk_mul_f32 v[132:133], v[132:133], v[156:157] op_sel_hi:[1,0]
	v_pk_mul_f32 v[130:131], v[130:131], v[156:157] op_sel_hi:[1,0]
	v_pk_mul_f32 v[128:129], v[128:129], v[156:157] op_sel_hi:[1,0]
	s_and_b64 vcc, exec, s[44:45]
	global_store_dwordx4 v[210:211], v[140:143], off offset:256
	s_cbranch_vccnz .LBB0_114
	v_mov_b64_e32 v[146:147], v[130:131]
	v_mov_b64_e32 v[142:143], v[134:135]
	s_and_b64 vcc, exec, s[42:43]
	v_mov_b64_e32 v[144:145], v[128:129]
	v_mov_b64_e32 v[140:141], v[132:133]
	s_cbranch_vccnz .LBB0_113
	v_pk_mul_f32 v[140:141], v[134:135], v[134:135]
	v_pk_mul_f32 v[142:143], v[132:133], v[132:133]
	s_mov_b32 s4, 0xf800000
	v_pk_mov_b32 v[144:145], v[142:143], v[140:141] op_sel:[1,0]
	v_mov_b32_e32 v143, v141
	v_pk_add_f32 v[140:141], v[144:145], v[142:143]
	v_pk_mul_f32 v[142:143], v[130:131], v[130:131]
	v_pk_mul_f32 v[144:145], v[128:129], v[128:129]
	v_mov_b32_e32 v146, v142
	v_mov_b32_e32 v147, v144
	v_mov_b32_e32 v144, v143
	v_pk_add_f32 v[142:143], v[146:147], v[144:145]
	v_add_f32_e32 v140, v140, v141
	v_add_f32_e32 v140, v143, v140
	v_add_f32_e32 v140, v142, v140
	v_and_b32_e32 v142, 64, v218
	v_xor_b32_e32 v141, 16, v218
	v_add_u32_e32 v142, 64, v142
	v_cmp_lt_i32_e32 vcc, v141, v142
	s_nop 1
	v_cndmask_b32_e32 v141, v218, v141, vcc
	v_lshlrev_b32_e32 v141, 2, v141
	ds_bpermute_b32 v141, v141, v140
	s_waitcnt lgkmcnt(0)
	v_add_f32_e32 v140, v140, v141
	v_xor_b32_e32 v141, 32, v218
	v_cmp_lt_i32_e32 vcc, v141, v142
	s_nop 1
	v_cndmask_b32_e32 v141, v218, v141, vcc
	v_lshlrev_b32_e32 v141, 2, v141
	ds_bpermute_b32 v141, v141, v140
	s_waitcnt lgkmcnt(0)
	v_add_f32_e32 v140, v140, v141
	v_fmamk_f32 v140, v140, 0x3d000000, v215
	v_mul_f32_e32 v141, 0x4f800000, v140
	v_cmp_gt_f32_e32 vcc, s4, v140
	s_nop 1
	v_cndmask_b32_e32 v140, v140, v141, vcc
	v_sqrt_f32_e32 v141, v140
	s_nop 0
	v_add_u32_e32 v142, -1, v141
	v_fma_f32 v143, -v142, v141, v140
	v_cmp_ge_f32_e64 s[4:5], 0, v143
	v_add_u32_e32 v143, 1, v141
	s_nop 0
	v_cndmask_b32_e64 v142, v141, v142, s[4:5]
	v_fma_f32 v141, -v143, v141, v140
	v_cmp_lt_f32_e64 s[4:5], 0, v141
	s_nop 1
	v_cndmask_b32_e64 v141, v142, v143, s[4:5]
	v_mul_f32_e32 v142, 0x37800000, v141
	v_cndmask_b32_e32 v141, v141, v142, vcc
	v_cmp_class_f32_e32 vcc, v140, v216
	s_nop 1
	v_cndmask_b32_e32 v140, v141, v140, vcc
	v_div_scale_f32 v141, s[4:5], v140, v140, 1.0
	v_rcp_f32_e32 v142, v141
	s_nop 0
	v_fma_f32 v143, -v141, v142, 1.0
	v_fmac_f32_e32 v142, v143, v142
	v_div_scale_f32 v143, vcc, 1.0, v140, 1.0
	v_mul_f32_e32 v144, v143, v142
	v_fma_f32 v145, -v141, v144, v143
	v_fmac_f32_e32 v144, v145, v142
	v_fma_f32 v141, -v141, v144, v143
	v_div_fmas_f32 v141, v141, v142, v144
	v_div_fixup_f32 v144, v141, v140, 1.0
	v_pk_mul_f32 v[140:141], v[132:133], v[144:145] op_sel_hi:[1,0]
	v_pk_mul_f32 v[142:143], v[134:135], v[144:145] op_sel_hi:[1,0]
	v_pk_mul_f32 v[148:149], v[128:129], v[144:145] op_sel_hi:[1,0]
	v_pk_mul_f32 v[144:145], v[130:131], v[144:145] op_sel_hi:[1,0]
	v_pk_mul_f32 v[142:143], v[192:193], v[142:143]
	v_pk_mul_f32 v[140:141], v[190:191], v[140:141]
	v_pk_mul_f32 v[146:147], v[188:189], v[144:145]
	v_pk_mul_f32 v[144:145], v[186:187], v[148:149]

.LBB0_122:
	s_cmp_eq_u32 s74, s73
	s_cbranch_scc1 .Lip_c2
	s_waitcnt vmcnt(8)
	v_add_f32_e32 v120, v136, v137
	v_add_f32_e32 v121, v138, v139
	v_add_f32_e32 v120, v120, v121
	v_fmamk_f32 v120, v120, 0x3a800000, v215
	s_mov_b32 s4, 0xf800000
	v_mul_f32_e32 v121, 0x4f800000, v120
	v_cmp_gt_f32_e32 vcc, s4, v120
	s_nop 1
	v_cndmask_b32_e32 v120, v120, v121, vcc
	v_sqrt_f32_e32 v121, v120
	s_nop 0
	v_add_u32_e32 v122, -1, v121
	v_fma_f32 v123, -v122, v121, v120
	v_cmp_ge_f32_e64 s[4:5], 0, v123
	v_add_u32_e32 v123, 1, v121
	s_nop 0
	v_cndmask_b32_e64 v122, v121, v122, s[4:5]
	v_fma_f32 v121, -v123, v121, v120
	v_cmp_lt_f32_e64 s[4:5], 0, v121
	s_nop 1
	v_cndmask_b32_e64 v121, v122, v123, s[4:5]
	v_mul_f32_e32 v122, 0x37800000, v121
	v_cndmask_b32_e32 v121, v121, v122, vcc
	v_cmp_class_f32_e32 vcc, v120, v216
	s_nop 1
	v_cndmask_b32_e32 v120, v121, v120, vcc
	v_div_scale_f32 v121, s[4:5], v120, v120, 1.0
	v_rcp_f32_e32 v122, v121
	s_mov_b64 s[4:5], -1
	v_fma_f32 v123, -v121, v122, 1.0
	v_fmac_f32_e32 v122, v123, v122
	v_div_scale_f32 v123, vcc, 1.0, v120, 1.0
	v_mul_f32_e32 v124, v123, v122
	v_fma_f32 v125, -v121, v124, v123
	v_fmac_f32_e32 v124, v125, v122
	v_fma_f32 v121, -v121, v124, v123
	v_div_fmas_f32 v121, v121, v122, v124
	v_div_fixup_f32 v136, v121, v120, 1.0
	ds_write_b32 v250, v136 offset:4096
	s_branch .Lip_j2

.Lip_j2:
	v_cvt_pk_bf16_f32 v120, v128, v129
	v_cvt_pk_bf16_f32 v121, v130, v131
	v_cvt_pk_bf16_f32 v122, v132, v133
	v_cvt_pk_bf16_f32 v123, v134, v135
	v_pk_mul_f32 v[114:115], v[114:115], v[136:137] op_sel_hi:[1,0]
	v_pk_mul_f32 v[112:113], v[112:113], v[136:137] op_sel_hi:[1,0]
	v_pk_mul_f32 v[110:111], v[110:111], v[136:137] op_sel_hi:[1,0]
	v_pk_mul_f32 v[108:109], v[108:109], v[136:137] op_sel_hi:[1,0]
	s_and_b64 vcc, exec, s[44:45]
	global_store_dwordx4 v[148:149], v[120:123], off offset:256
	s_cbranch_vccnz .LBB0_126
	v_mov_b64_e32 v[126:127], v[110:111]
	v_mov_b64_e32 v[122:123], v[114:115]
	s_and_b64 vcc, exec, s[42:43]
	v_mov_b64_e32 v[124:125], v[108:109]
	v_mov_b64_e32 v[120:121], v[112:113]
	s_cbranch_vccnz .LBB0_125
	v_pk_mul_f32 v[120:121], v[114:115], v[114:115]
	v_pk_mul_f32 v[122:123], v[112:113], v[112:113]
	s_mov_b32 s4, 0xf800000
	v_pk_mov_b32 v[124:125], v[122:123], v[120:121] op_sel:[1,0]
	v_mov_b32_e32 v123, v121
	v_pk_add_f32 v[120:121], v[124:125], v[122:123]
	v_pk_mul_f32 v[122:123], v[110:111], v[110:111]
	v_pk_mul_f32 v[124:125], v[108:109], v[108:109]
	v_mov_b32_e32 v126, v122
	v_mov_b32_e32 v127, v124
	v_mov_b32_e32 v124, v123
	v_pk_add_f32 v[122:123], v[126:127], v[124:125]
	v_add_f32_e32 v120, v120, v121
	v_add_f32_e32 v120, v123, v120
	v_add_f32_e32 v120, v122, v120
	v_and_b32_e32 v122, 64, v218
	v_xor_b32_e32 v121, 16, v218
	v_add_u32_e32 v122, 64, v122
	v_cmp_lt_i32_e32 vcc, v121, v122
	s_nop 1
	v_cndmask_b32_e32 v121, v218, v121, vcc
	v_lshlrev_b32_e32 v121, 2, v121
	ds_bpermute_b32 v121, v121, v120
	s_waitcnt lgkmcnt(0)
	v_add_f32_e32 v120, v120, v121
	v_xor_b32_e32 v121, 32, v218
	v_cmp_lt_i32_e32 vcc, v121, v122
	s_nop 1
	v_cndmask_b32_e32 v121, v218, v121, vcc
	v_lshlrev_b32_e32 v121, 2, v121
	ds_bpermute_b32 v121, v121, v120
	s_waitcnt lgkmcnt(0)
	v_add_f32_e32 v120, v120, v121
	v_fmamk_f32 v120, v120, 0x3d000000, v215
	v_mul_f32_e32 v121, 0x4f800000, v120
	v_cmp_gt_f32_e32 vcc, s4, v120
	s_nop 1
	v_cndmask_b32_e32 v120, v120, v121, vcc
	v_sqrt_f32_e32 v121, v120
	s_nop 0
	v_add_u32_e32 v122, -1, v121
	v_fma_f32 v123, -v122, v121, v120
	v_cmp_ge_f32_e64 s[4:5], 0, v123
	v_add_u32_e32 v123, 1, v121
	s_nop 0
	v_cndmask_b32_e64 v122, v121, v122, s[4:5]
	v_fma_f32 v121, -v123, v121, v120
	v_cmp_lt_f32_e64 s[4:5], 0, v121
	s_nop 1
	v_cndmask_b32_e64 v121, v122, v123, s[4:5]
	v_mul_f32_e32 v122, 0x37800000, v121
	v_cndmask_b32_e32 v121, v121, v122, vcc
	v_cmp_class_f32_e32 vcc, v120, v216
	s_nop 1
	v_cndmask_b32_e32 v120, v121, v120, vcc
	v_div_scale_f32 v121, s[4:5], v120, v120, 1.0
	v_rcp_f32_e32 v122, v121
	s_nop 0
	v_fma_f32 v123, -v121, v122, 1.0
	v_fmac_f32_e32 v122, v123, v122
	v_div_scale_f32 v123, vcc, 1.0, v120, 1.0
	v_mul_f32_e32 v124, v123, v122
	v_fma_f32 v125, -v121, v124, v123
	v_fmac_f32_e32 v124, v125, v122
	v_fma_f32 v121, -v121, v124, v123
	v_div_fmas_f32 v121, v121, v122, v124
	v_div_fixup_f32 v124, v121, v120, 1.0
	v_pk_mul_f32 v[120:121], v[112:113], v[124:125] op_sel_hi:[1,0]
	v_pk_mul_f32 v[122:123], v[114:115], v[124:125] op_sel_hi:[1,0]
	v_pk_mul_f32 v[128:129], v[108:109], v[124:125] op_sel_hi:[1,0]
	v_pk_mul_f32 v[124:125], v[110:111], v[124:125] op_sel_hi:[1,0]
	v_pk_mul_f32 v[122:123], v[192:193], v[122:123]
	v_pk_mul_f32 v[120:121], v[190:191], v[120:121]
	v_pk_mul_f32 v[126:127], v[188:189], v[124:125]
	v_pk_mul_f32 v[124:125], v[186:187], v[128:129]

.LBB0_134:
	s_cmp_eq_u32 s74, s73
	s_cbranch_scc1 .Lip_c3
	s_waitcnt vmcnt(9)
	v_add_f32_e32 v100, v116, v117
	v_add_f32_e32 v101, v118, v119
	v_add_f32_e32 v100, v100, v101
	v_fmamk_f32 v100, v100, 0x3a800000, v215
	s_mov_b32 s4, 0xf800000
	v_mul_f32_e32 v101, 0x4f800000, v100
	v_cmp_gt_f32_e32 vcc, s4, v100
	s_nop 1
	v_cndmask_b32_e32 v100, v100, v101, vcc
	v_sqrt_f32_e32 v101, v100
	s_nop 0
	v_add_u32_e32 v102, -1, v101
	v_fma_f32 v103, -v102, v101, v100
	v_cmp_ge_f32_e64 s[4:5], 0, v103
	v_add_u32_e32 v103, 1, v101
	s_nop 0
	v_cndmask_b32_e64 v102, v101, v102, s[4:5]
	v_fma_f32 v101, -v103, v101, v100
	v_cmp_lt_f32_e64 s[4:5], 0, v101
	s_nop 1
	v_cndmask_b32_e64 v101, v102, v103, s[4:5]
	v_mul_f32_e32 v102, 0x37800000, v101
	v_cndmask_b32_e32 v101, v101, v102, vcc
	v_cmp_class_f32_e32 vcc, v100, v216
	s_nop 1
	v_cndmask_b32_e32 v100, v101, v100, vcc
	v_div_scale_f32 v101, s[4:5], v100, v100, 1.0
	v_rcp_f32_e32 v102, v101
	s_mov_b64 s[4:5], -1
	v_fma_f32 v103, -v101, v102, 1.0
	v_fmac_f32_e32 v102, v103, v102
	v_div_scale_f32 v103, vcc, 1.0, v100, 1.0
	v_mul_f32_e32 v104, v103, v102
	v_fma_f32 v105, -v101, v104, v103
	v_fmac_f32_e32 v104, v105, v102
	v_fma_f32 v101, -v101, v104, v103
	v_div_fmas_f32 v101, v101, v102, v104
	v_div_fixup_f32 v116, v101, v100, 1.0
	ds_write_b32 v250, v116 offset:6144
	s_branch .Lip_j3

.Lip_j3:
	v_cvt_pk_bf16_f32 v100, v108, v109
	v_cvt_pk_bf16_f32 v101, v110, v111
	v_cvt_pk_bf16_f32 v102, v112, v113
	v_cvt_pk_bf16_f32 v103, v114, v115
	v_pk_mul_f32 v[94:95], v[94:95], v[116:117] op_sel_hi:[1,0]
	v_pk_mul_f32 v[92:93], v[92:93], v[116:117] op_sel_hi:[1,0]
	v_pk_mul_f32 v[90:91], v[90:91], v[116:117] op_sel_hi:[1,0]
	v_pk_mul_f32 v[88:89], v[88:89], v[116:117] op_sel_hi:[1,0]
	s_and_b64 vcc, exec, s[44:45]
	global_store_dwordx4 v[128:129], v[100:103], off offset:256
	s_cbranch_vccnz .LBB0_138
	v_mov_b64_e32 v[106:107], v[90:91]
	v_mov_b64_e32 v[102:103], v[94:95]
	s_and_b64 vcc, exec, s[42:43]
	v_mov_b64_e32 v[104:105], v[88:89]
	v_mov_b64_e32 v[100:101], v[92:93]
	s_cbranch_vccnz .LBB0_137
	v_pk_mul_f32 v[100:101], v[94:95], v[94:95]
	v_pk_mul_f32 v[102:103], v[92:93], v[92:93]
	s_mov_b32 s4, 0xf800000
	v_pk_mov_b32 v[104:105], v[102:103], v[100:101] op_sel:[1,0]
	v_mov_b32_e32 v103, v101
	v_pk_add_f32 v[100:101], v[104:105], v[102:103]
	v_pk_mul_f32 v[102:103], v[90:91], v[90:91]
	v_pk_mul_f32 v[104:105], v[88:89], v[88:89]
	v_mov_b32_e32 v106, v102
	v_mov_b32_e32 v107, v104
	v_mov_b32_e32 v104, v103
	v_pk_add_f32 v[102:103], v[106:107], v[104:105]
	v_add_f32_e32 v100, v100, v101
	v_add_f32_e32 v100, v103, v100
	v_add_f32_e32 v100, v102, v100
	v_and_b32_e32 v102, 64, v218
	v_xor_b32_e32 v101, 16, v218
	v_add_u32_e32 v102, 64, v102
	v_cmp_lt_i32_e32 vcc, v101, v102
	s_nop 1
	v_cndmask_b32_e32 v101, v218, v101, vcc
	v_lshlrev_b32_e32 v101, 2, v101
	ds_bpermute_b32 v101, v101, v100
	s_waitcnt lgkmcnt(0)
	v_add_f32_e32 v100, v100, v101
	v_xor_b32_e32 v101, 32, v218
	v_cmp_lt_i32_e32 vcc, v101, v102
	s_nop 1
	v_cndmask_b32_e32 v101, v218, v101, vcc
	v_lshlrev_b32_e32 v101, 2, v101
	ds_bpermute_b32 v101, v101, v100
	s_waitcnt lgkmcnt(0)
	v_add_f32_e32 v100, v100, v101
	v_fmamk_f32 v100, v100, 0x3d000000, v215
	v_mul_f32_e32 v101, 0x4f800000, v100
	v_cmp_gt_f32_e32 vcc, s4, v100
	s_nop 1
	v_cndmask_b32_e32 v100, v100, v101, vcc
	v_sqrt_f32_e32 v101, v100
	s_nop 0
	v_add_u32_e32 v102, -1, v101
	v_fma_f32 v103, -v102, v101, v100
	v_cmp_ge_f32_e64 s[4:5], 0, v103
	v_add_u32_e32 v103, 1, v101
	s_nop 0
	v_cndmask_b32_e64 v102, v101, v102, s[4:5]
	v_fma_f32 v101, -v103, v101, v100
	v_cmp_lt_f32_e64 s[4:5], 0, v101
	s_nop 1
	v_cndmask_b32_e64 v101, v102, v103, s[4:5]
	v_mul_f32_e32 v102, 0x37800000, v101
	v_cndmask_b32_e32 v101, v101, v102, vcc
	v_cmp_class_f32_e32 vcc, v100, v216
	s_nop 1
	v_cndmask_b32_e32 v100, v101, v100, vcc
	v_div_scale_f32 v101, s[4:5], v100, v100, 1.0
	v_rcp_f32_e32 v102, v101
	s_nop 0
	v_fma_f32 v103, -v101, v102, 1.0
	v_fmac_f32_e32 v102, v103, v102
	v_div_scale_f32 v103, vcc, 1.0, v100, 1.0
	v_mul_f32_e32 v104, v103, v102
	v_fma_f32 v105, -v101, v104, v103
	v_fmac_f32_e32 v104, v105, v102
	v_fma_f32 v101, -v101, v104, v103
	v_div_fmas_f32 v101, v101, v102, v104
	v_div_fixup_f32 v104, v101, v100, 1.0
	v_pk_mul_f32 v[100:101], v[92:93], v[104:105] op_sel_hi:[1,0]
	v_pk_mul_f32 v[102:103], v[94:95], v[104:105] op_sel_hi:[1,0]
	v_pk_mul_f32 v[108:109], v[88:89], v[104:105] op_sel_hi:[1,0]
	v_pk_mul_f32 v[104:105], v[90:91], v[104:105] op_sel_hi:[1,0]
	v_pk_mul_f32 v[102:103], v[192:193], v[102:103]
	v_pk_mul_f32 v[100:101], v[190:191], v[100:101]
	v_pk_mul_f32 v[106:107], v[188:189], v[104:105]
	v_pk_mul_f32 v[104:105], v[186:187], v[108:109]

.LBB0_146:
	s_cmp_eq_u32 s74, s73
	s_cbranch_scc1 .Lip_c4
	s_waitcnt vmcnt(10)
	v_add_f32_e32 v80, v96, v97
	v_add_f32_e32 v81, v98, v99
	v_add_f32_e32 v80, v80, v81
	v_fmamk_f32 v80, v80, 0x3a800000, v215
	s_mov_b32 s4, 0xf800000
	v_mul_f32_e32 v81, 0x4f800000, v80
	v_cmp_gt_f32_e32 vcc, s4, v80
	s_nop 1
	v_cndmask_b32_e32 v80, v80, v81, vcc
	v_sqrt_f32_e32 v81, v80
	s_nop 0
	v_add_u32_e32 v82, -1, v81
	v_fma_f32 v83, -v82, v81, v80
	v_cmp_ge_f32_e64 s[4:5], 0, v83
	v_add_u32_e32 v83, 1, v81
	s_nop 0
	v_cndmask_b32_e64 v82, v81, v82, s[4:5]
	v_fma_f32 v81, -v83, v81, v80
	v_cmp_lt_f32_e64 s[4:5], 0, v81
	s_nop 1
	v_cndmask_b32_e64 v81, v82, v83, s[4:5]
	v_mul_f32_e32 v82, 0x37800000, v81
	v_cndmask_b32_e32 v81, v81, v82, vcc
	v_cmp_class_f32_e32 vcc, v80, v216
	s_nop 1
	v_cndmask_b32_e32 v80, v81, v80, vcc
	v_div_scale_f32 v81, s[4:5], v80, v80, 1.0
	v_rcp_f32_e32 v82, v81
	s_mov_b64 s[4:5], -1
	v_fma_f32 v83, -v81, v82, 1.0
	v_fmac_f32_e32 v82, v83, v82
	v_div_scale_f32 v83, vcc, 1.0, v80, 1.0
	v_mul_f32_e32 v84, v83, v82
	v_fma_f32 v85, -v81, v84, v83
	v_fmac_f32_e32 v84, v85, v82
	v_fma_f32 v81, -v81, v84, v83
	v_div_fmas_f32 v81, v81, v82, v84
	v_div_fixup_f32 v96, v81, v80, 1.0
	ds_write_b32 v250, v96 offset:8192
	s_branch .Lip_j4

.Lip_j4:
	v_cvt_pk_bf16_f32 v80, v88, v89
	v_cvt_pk_bf16_f32 v81, v90, v91
	v_cvt_pk_bf16_f32 v82, v92, v93
	v_cvt_pk_bf16_f32 v83, v94, v95
	v_pk_mul_f32 v[74:75], v[74:75], v[96:97] op_sel_hi:[1,0]
	v_pk_mul_f32 v[72:73], v[72:73], v[96:97] op_sel_hi:[1,0]
	v_pk_mul_f32 v[70:71], v[70:71], v[96:97] op_sel_hi:[1,0]
	v_pk_mul_f32 v[68:69], v[68:69], v[96:97] op_sel_hi:[1,0]
	s_and_b64 vcc, exec, s[44:45]
	global_store_dwordx4 v[108:109], v[80:83], off offset:256
	s_cbranch_vccnz .LBB0_150
	v_mov_b64_e32 v[86:87], v[70:71]
	v_mov_b64_e32 v[82:83], v[74:75]
	s_and_b64 vcc, exec, s[42:43]
	v_mov_b64_e32 v[84:85], v[68:69]
	v_mov_b64_e32 v[80:81], v[72:73]
	s_cbranch_vccnz .LBB0_149
	v_pk_mul_f32 v[80:81], v[74:75], v[74:75]
	v_pk_mul_f32 v[82:83], v[72:73], v[72:73]
	s_mov_b32 s4, 0xf800000
	v_pk_mov_b32 v[84:85], v[82:83], v[80:81] op_sel:[1,0]
	v_mov_b32_e32 v83, v81
	v_pk_add_f32 v[80:81], v[84:85], v[82:83]
	v_pk_mul_f32 v[82:83], v[70:71], v[70:71]
	v_pk_mul_f32 v[84:85], v[68:69], v[68:69]
	v_mov_b32_e32 v86, v82
	v_mov_b32_e32 v87, v84
	v_mov_b32_e32 v84, v83
	v_pk_add_f32 v[82:83], v[86:87], v[84:85]
	v_add_f32_e32 v80, v80, v81
	v_add_f32_e32 v80, v83, v80
	v_add_f32_e32 v80, v82, v80
	v_and_b32_e32 v82, 64, v218
	v_xor_b32_e32 v81, 16, v218
	v_add_u32_e32 v82, 64, v82
	v_cmp_lt_i32_e32 vcc, v81, v82
	s_nop 1
	v_cndmask_b32_e32 v81, v218, v81, vcc
	v_lshlrev_b32_e32 v81, 2, v81
	ds_bpermute_b32 v81, v81, v80
	s_waitcnt lgkmcnt(0)
	v_add_f32_e32 v80, v80, v81
	v_xor_b32_e32 v81, 32, v218
	v_cmp_lt_i32_e32 vcc, v81, v82
	s_nop 1
	v_cndmask_b32_e32 v81, v218, v81, vcc
	v_lshlrev_b32_e32 v81, 2, v81
	ds_bpermute_b32 v81, v81, v80
	s_waitcnt lgkmcnt(0)
	v_add_f32_e32 v80, v80, v81
	v_fmamk_f32 v80, v80, 0x3d000000, v215
	v_mul_f32_e32 v81, 0x4f800000, v80
	v_cmp_gt_f32_e32 vcc, s4, v80
	s_nop 1
	v_cndmask_b32_e32 v80, v80, v81, vcc
	v_sqrt_f32_e32 v81, v80
	s_nop 0
	v_add_u32_e32 v82, -1, v81
	v_fma_f32 v83, -v82, v81, v80
	v_cmp_ge_f32_e64 s[4:5], 0, v83
	v_add_u32_e32 v83, 1, v81
	s_nop 0
	v_cndmask_b32_e64 v82, v81, v82, s[4:5]
	v_fma_f32 v81, -v83, v81, v80
	v_cmp_lt_f32_e64 s[4:5], 0, v81
	s_nop 1
	v_cndmask_b32_e64 v81, v82, v83, s[4:5]
	v_mul_f32_e32 v82, 0x37800000, v81
	v_cndmask_b32_e32 v81, v81, v82, vcc
	v_cmp_class_f32_e32 vcc, v80, v216
	s_nop 1
	v_cndmask_b32_e32 v80, v81, v80, vcc
	v_div_scale_f32 v81, s[4:5], v80, v80, 1.0
	v_rcp_f32_e32 v82, v81
	s_nop 0
	v_fma_f32 v83, -v81, v82, 1.0
	v_fmac_f32_e32 v82, v83, v82
	v_div_scale_f32 v83, vcc, 1.0, v80, 1.0
	v_mul_f32_e32 v84, v83, v82
	v_fma_f32 v85, -v81, v84, v83
	v_fmac_f32_e32 v84, v85, v82
	v_fma_f32 v81, -v81, v84, v83
	v_div_fmas_f32 v81, v81, v82, v84
	v_div_fixup_f32 v84, v81, v80, 1.0
	v_pk_mul_f32 v[80:81], v[72:73], v[84:85] op_sel_hi:[1,0]
	v_pk_mul_f32 v[82:83], v[74:75], v[84:85] op_sel_hi:[1,0]
	v_pk_mul_f32 v[88:89], v[68:69], v[84:85] op_sel_hi:[1,0]
	v_pk_mul_f32 v[84:85], v[70:71], v[84:85] op_sel_hi:[1,0]
	v_pk_mul_f32 v[82:83], v[192:193], v[82:83]
	v_pk_mul_f32 v[80:81], v[190:191], v[80:81]
	v_pk_mul_f32 v[86:87], v[188:189], v[84:85]
	v_pk_mul_f32 v[84:85], v[186:187], v[88:89]

.LBB0_158:
	s_cmp_eq_u32 s74, s73
	s_cbranch_scc1 .Lip_c5
	s_waitcnt vmcnt(11)
	v_add_f32_e32 v56, v76, v77
	v_add_f32_e32 v57, v78, v79
	v_add_f32_e32 v56, v56, v57
	v_fmamk_f32 v56, v56, 0x3a800000, v215
	s_mov_b32 s4, 0xf800000
	v_mul_f32_e32 v57, 0x4f800000, v56
	v_cmp_gt_f32_e32 vcc, s4, v56
	s_nop 1
	v_cndmask_b32_e32 v56, v56, v57, vcc
	v_sqrt_f32_e32 v57, v56
	s_nop 0
	v_add_u32_e32 v58, -1, v57
	v_fma_f32 v59, -v58, v57, v56
	v_cmp_ge_f32_e64 s[4:5], 0, v59
	v_add_u32_e32 v59, 1, v57
	s_nop 0
	v_cndmask_b32_e64 v58, v57, v58, s[4:5]
	v_fma_f32 v57, -v59, v57, v56
	v_cmp_lt_f32_e64 s[4:5], 0, v57
	s_nop 1
	v_cndmask_b32_e64 v57, v58, v59, s[4:5]
	v_mul_f32_e32 v58, 0x37800000, v57
	v_cndmask_b32_e32 v57, v57, v58, vcc
	v_cmp_class_f32_e32 vcc, v56, v216
	s_nop 1
	v_cndmask_b32_e32 v56, v57, v56, vcc
	v_div_scale_f32 v57, s[4:5], v56, v56, 1.0
	v_rcp_f32_e32 v58, v57
	s_mov_b64 s[4:5], -1
	v_fma_f32 v59, -v57, v58, 1.0
	v_fmac_f32_e32 v58, v59, v58
	v_div_scale_f32 v59, vcc, 1.0, v56, 1.0
	v_mul_f32_e32 v60, v59, v58
	v_fma_f32 v61, -v57, v60, v59
	v_fmac_f32_e32 v60, v61, v58
	v_fma_f32 v57, -v57, v60, v59
	v_div_fmas_f32 v57, v57, v58, v60
	v_div_fixup_f32 v76, v57, v56, 1.0
	ds_write_b32 v250, v76 offset:10240
	s_branch .Lip_j5

.Lip_j5:
	v_cvt_pk_bf16_f32 v56, v68, v69
	v_cvt_pk_bf16_f32 v57, v70, v71
	v_cvt_pk_bf16_f32 v58, v72, v73
	v_cvt_pk_bf16_f32 v59, v74, v75
	v_pk_mul_f32 v[54:55], v[54:55], v[76:77] op_sel_hi:[1,0]
	v_pk_mul_f32 v[52:53], v[52:53], v[76:77] op_sel_hi:[1,0]
	v_pk_mul_f32 v[50:51], v[50:51], v[76:77] op_sel_hi:[1,0]
	v_pk_mul_f32 v[48:49], v[48:49], v[76:77] op_sel_hi:[1,0]
	s_and_b64 vcc, exec, s[44:45]
	global_store_dwordx4 v[88:89], v[56:59], off offset:256
	s_cbranch_vccnz .LBB0_162
	v_mov_b64_e32 v[62:63], v[50:51]
	v_mov_b64_e32 v[58:59], v[54:55]
	s_and_b64 vcc, exec, s[42:43]
	v_mov_b64_e32 v[60:61], v[48:49]
	v_mov_b64_e32 v[56:57], v[52:53]
	s_cbranch_vccnz .LBB0_161
	v_pk_mul_f32 v[56:57], v[54:55], v[54:55]
	v_pk_mul_f32 v[58:59], v[52:53], v[52:53]
	s_mov_b32 s4, 0xf800000
	v_pk_mov_b32 v[60:61], v[58:59], v[56:57] op_sel:[1,0]
	v_mov_b32_e32 v59, v57
	v_pk_add_f32 v[56:57], v[60:61], v[58:59]
	v_pk_mul_f32 v[58:59], v[50:51], v[50:51]
	v_pk_mul_f32 v[60:61], v[48:49], v[48:49]
	v_mov_b32_e32 v62, v58
	v_mov_b32_e32 v63, v60
	v_mov_b32_e32 v60, v59
	v_pk_add_f32 v[58:59], v[62:63], v[60:61]
	v_add_f32_e32 v56, v56, v57
	v_add_f32_e32 v56, v59, v56
	v_add_f32_e32 v56, v58, v56
	v_and_b32_e32 v58, 64, v218
	v_xor_b32_e32 v57, 16, v218
	v_add_u32_e32 v58, 64, v58
	v_cmp_lt_i32_e32 vcc, v57, v58
	s_nop 1
	v_cndmask_b32_e32 v57, v218, v57, vcc
	v_lshlrev_b32_e32 v57, 2, v57
	ds_bpermute_b32 v57, v57, v56
	s_waitcnt lgkmcnt(0)
	v_add_f32_e32 v56, v56, v57
	v_xor_b32_e32 v57, 32, v218
	v_cmp_lt_i32_e32 vcc, v57, v58
	s_nop 1
	v_cndmask_b32_e32 v57, v218, v57, vcc
	v_lshlrev_b32_e32 v57, 2, v57
	ds_bpermute_b32 v57, v57, v56
	s_waitcnt lgkmcnt(0)
	v_add_f32_e32 v56, v56, v57
	v_fmamk_f32 v56, v56, 0x3d000000, v215
	v_mul_f32_e32 v57, 0x4f800000, v56
	v_cmp_gt_f32_e32 vcc, s4, v56
	s_nop 1
	v_cndmask_b32_e32 v56, v56, v57, vcc
	v_sqrt_f32_e32 v57, v56
	s_nop 0
	v_add_u32_e32 v58, -1, v57
	v_fma_f32 v59, -v58, v57, v56
	v_cmp_ge_f32_e64 s[4:5], 0, v59
	v_add_u32_e32 v59, 1, v57
	s_nop 0
	v_cndmask_b32_e64 v58, v57, v58, s[4:5]
	v_fma_f32 v57, -v59, v57, v56
	v_cmp_lt_f32_e64 s[4:5], 0, v57
	s_nop 1
	v_cndmask_b32_e64 v57, v58, v59, s[4:5]
	v_mul_f32_e32 v58, 0x37800000, v57
	v_cndmask_b32_e32 v57, v57, v58, vcc
	v_cmp_class_f32_e32 vcc, v56, v216
	s_nop 1
	v_cndmask_b32_e32 v56, v57, v56, vcc
	v_div_scale_f32 v57, s[4:5], v56, v56, 1.0
	v_rcp_f32_e32 v58, v57
	s_nop 0
	v_fma_f32 v59, -v57, v58, 1.0
	v_fmac_f32_e32 v58, v59, v58
	v_div_scale_f32 v59, vcc, 1.0, v56, 1.0
	v_mul_f32_e32 v60, v59, v58
	v_fma_f32 v61, -v57, v60, v59
	v_fmac_f32_e32 v60, v61, v58
	v_fma_f32 v57, -v57, v60, v59
	v_div_fmas_f32 v57, v57, v58, v60
	v_div_fixup_f32 v60, v57, v56, 1.0
	v_pk_mul_f32 v[56:57], v[52:53], v[60:61] op_sel_hi:[1,0]
	v_pk_mul_f32 v[58:59], v[54:55], v[60:61] op_sel_hi:[1,0]
	v_pk_mul_f32 v[68:69], v[48:49], v[60:61] op_sel_hi:[1,0]
	v_pk_mul_f32 v[60:61], v[50:51], v[60:61] op_sel_hi:[1,0]
	v_pk_mul_f32 v[58:59], v[192:193], v[58:59]
	v_pk_mul_f32 v[56:57], v[190:191], v[56:57]
	v_pk_mul_f32 v[62:63], v[188:189], v[60:61]
	v_pk_mul_f32 v[60:61], v[186:187], v[68:69]

.LBB0_170:
	s_cmp_eq_u32 s74, s73
	s_cbranch_scc1 .Lip_c6
	s_waitcnt vmcnt(12)
	v_add_f32_e32 v36, v64, v65
	v_add_f32_e32 v37, v66, v67
	v_add_f32_e32 v36, v36, v37
	v_fmamk_f32 v36, v36, 0x3a800000, v215
	s_mov_b32 s4, 0xf800000
	v_mul_f32_e32 v37, 0x4f800000, v36
	v_cmp_gt_f32_e32 vcc, s4, v36
	s_nop 1
	v_cndmask_b32_e32 v36, v36, v37, vcc
	v_sqrt_f32_e32 v37, v36
	s_nop 0
	v_add_u32_e32 v38, -1, v37
	v_fma_f32 v39, -v38, v37, v36
	v_cmp_ge_f32_e64 s[4:5], 0, v39
	v_add_u32_e32 v39, 1, v37
	s_nop 0
	v_cndmask_b32_e64 v38, v37, v38, s[4:5]
	v_fma_f32 v37, -v39, v37, v36
	v_cmp_lt_f32_e64 s[4:5], 0, v37
	s_nop 1
	v_cndmask_b32_e64 v37, v38, v39, s[4:5]
	v_mul_f32_e32 v38, 0x37800000, v37
	v_cndmask_b32_e32 v37, v37, v38, vcc
	v_cmp_class_f32_e32 vcc, v36, v216
	s_nop 1
	v_cndmask_b32_e32 v36, v37, v36, vcc
	v_div_scale_f32 v37, s[4:5], v36, v36, 1.0
	v_rcp_f32_e32 v38, v37
	s_mov_b64 s[4:5], -1
	v_fma_f32 v39, -v37, v38, 1.0
	v_fmac_f32_e32 v38, v39, v38
	v_div_scale_f32 v39, vcc, 1.0, v36, 1.0
	v_mul_f32_e32 v40, v39, v38
	v_fma_f32 v41, -v37, v40, v39
	v_fmac_f32_e32 v40, v41, v38
	v_fma_f32 v37, -v37, v40, v39
	v_div_fmas_f32 v37, v37, v38, v40
	v_div_fixup_f32 v56, v37, v36, 1.0
	ds_write_b32 v250, v56 offset:12288
	s_branch .Lip_j6
.Lip_c6:
	v_mov_b32_e32 v56, v64
	s_mov_b64 s[4:5], -1
.Lip_j6:
	v_cvt_pk_bf16_f32 v36, v48, v49
	v_cvt_pk_bf16_f32 v37, v50, v51
	v_cvt_pk_bf16_f32 v38, v52, v53
	v_cvt_pk_bf16_f32 v39, v54, v55
	v_pk_mul_f32 v[34:35], v[34:35], v[56:57] op_sel_hi:[1,0]
	v_pk_mul_f32 v[32:33], v[32:33], v[56:57] op_sel_hi:[1,0]
	v_pk_mul_f32 v[30:31], v[30:31], v[56:57] op_sel_hi:[1,0]
	v_pk_mul_f32 v[28:29], v[28:29], v[56:57] op_sel_hi:[1,0]
	s_and_b64 vcc, exec, s[44:45]
	global_store_dwordx4 v[68:69], v[36:39], off offset:256
	s_cbranch_vccnz .LBB0_174
	v_mov_b64_e32 v[42:43], v[30:31]
	v_mov_b64_e32 v[38:39], v[34:35]
	s_and_b64 vcc, exec, s[42:43]
	v_mov_b64_e32 v[40:41], v[28:29]
	v_mov_b64_e32 v[36:37], v[32:33]
	s_cbranch_vccnz .LBB0_173
	v_pk_mul_f32 v[36:37], v[34:35], v[34:35]
	v_pk_mul_f32 v[38:39], v[32:33], v[32:33]
	s_mov_b32 s4, 0xf800000
	v_pk_mov_b32 v[40:41], v[38:39], v[36:37] op_sel:[1,0]
	v_mov_b32_e32 v39, v37
	v_pk_add_f32 v[36:37], v[40:41], v[38:39]
	v_pk_mul_f32 v[38:39], v[30:31], v[30:31]
	v_pk_mul_f32 v[40:41], v[28:29], v[28:29]
	v_mov_b32_e32 v42, v38
	v_mov_b32_e32 v43, v40
	v_mov_b32_e32 v40, v39
	v_pk_add_f32 v[38:39], v[42:43], v[40:41]
	v_add_f32_e32 v36, v36, v37
	v_add_f32_e32 v36, v39, v36
	v_add_f32_e32 v36, v38, v36
	v_and_b32_e32 v38, 64, v218
	v_xor_b32_e32 v37, 16, v218
	v_add_u32_e32 v38, 64, v38
	v_cmp_lt_i32_e32 vcc, v37, v38
	s_nop 1
	v_cndmask_b32_e32 v37, v218, v37, vcc
	v_lshlrev_b32_e32 v37, 2, v37
	ds_bpermute_b32 v37, v37, v36
	s_waitcnt lgkmcnt(0)
	v_add_f32_e32 v36, v36, v37
	v_xor_b32_e32 v37, 32, v218
	v_cmp_lt_i32_e32 vcc, v37, v38
	s_nop 1
	v_cndmask_b32_e32 v37, v218, v37, vcc
	v_lshlrev_b32_e32 v37, 2, v37
	ds_bpermute_b32 v37, v37, v36
	s_waitcnt lgkmcnt(0)
	v_add_f32_e32 v36, v36, v37
	v_fmamk_f32 v36, v36, 0x3d000000, v215
	v_mul_f32_e32 v37, 0x4f800000, v36
	v_cmp_gt_f32_e32 vcc, s4, v36
	s_nop 1
	v_cndmask_b32_e32 v36, v36, v37, vcc
	v_sqrt_f32_e32 v37, v36
	s_nop 0
	v_add_u32_e32 v38, -1, v37
	v_fma_f32 v39, -v38, v37, v36
	v_cmp_ge_f32_e64 s[4:5], 0, v39
	v_add_u32_e32 v39, 1, v37
	s_nop 0
	v_cndmask_b32_e64 v38, v37, v38, s[4:5]
	v_fma_f32 v37, -v39, v37, v36
	v_cmp_lt_f32_e64 s[4:5], 0, v37
	s_nop 1
	v_cndmask_b32_e64 v37, v38, v39, s[4:5]
	v_mul_f32_e32 v38, 0x37800000, v37
	v_cndmask_b32_e32 v37, v37, v38, vcc
	v_cmp_class_f32_e32 vcc, v36, v216
	s_nop 1
	v_cndmask_b32_e32 v36, v37, v36, vcc
	v_div_scale_f32 v37, s[4:5], v36, v36, 1.0
	v_rcp_f32_e32 v38, v37
	s_nop 0
	v_fma_f32 v39, -v37, v38, 1.0
	v_fmac_f32_e32 v38, v39, v38
	v_div_scale_f32 v39, vcc, 1.0, v36, 1.0
	v_mul_f32_e32 v40, v39, v38
	v_fma_f32 v41, -v37, v40, v39
	v_fmac_f32_e32 v40, v41, v38
	v_fma_f32 v37, -v37, v40, v39
	v_div_fmas_f32 v37, v37, v38, v40
	v_div_fixup_f32 v40, v37, v36, 1.0
	v_pk_mul_f32 v[36:37], v[32:33], v[40:41] op_sel_hi:[1,0]
	v_pk_mul_f32 v[38:39], v[34:35], v[40:41] op_sel_hi:[1,0]
	v_pk_mul_f32 v[48:49], v[28:29], v[40:41] op_sel_hi:[1,0]
	v_pk_mul_f32 v[40:41], v[30:31], v[40:41] op_sel_hi:[1,0]
	v_pk_mul_f32 v[38:39], v[192:193], v[38:39]
	v_pk_mul_f32 v[36:37], v[190:191], v[36:37]
	v_pk_mul_f32 v[42:43], v[188:189], v[40:41]
	v_pk_mul_f32 v[40:41], v[186:187], v[48:49]

.LBB0_182:
	s_cmp_eq_u32 s74, s73
	s_cbranch_scc1 .Lip_c7
	s_waitcnt vmcnt(13)
	v_add_f32_e32 v20, v44, v45
	v_add_f32_e32 v21, v46, v47
	v_add_f32_e32 v20, v20, v21
	v_fmamk_f32 v20, v20, 0x3a800000, v215
	s_mov_b32 s4, 0xf800000
	v_mul_f32_e32 v21, 0x4f800000, v20
	v_cmp_gt_f32_e32 vcc, s4, v20
	s_nop 1
	v_cndmask_b32_e32 v20, v20, v21, vcc
	v_sqrt_f32_e32 v21, v20
	s_nop 0
	v_add_u32_e32 v22, -1, v21
	v_fma_f32 v23, -v22, v21, v20
	v_cmp_ge_f32_e64 s[4:5], 0, v23
	v_add_u32_e32 v23, 1, v21
	s_nop 0
	v_cndmask_b32_e64 v22, v21, v22, s[4:5]
	v_fma_f32 v21, -v23, v21, v20
	v_cmp_lt_f32_e64 s[4:5], 0, v21
	s_nop 1
	v_cndmask_b32_e64 v21, v22, v23, s[4:5]
	v_mul_f32_e32 v22, 0x37800000, v21
	v_cndmask_b32_e32 v21, v21, v22, vcc
	v_cmp_class_f32_e32 vcc, v20, v216
	s_nop 1
	v_cndmask_b32_e32 v20, v21, v20, vcc
	v_div_scale_f32 v21, s[4:5], v20, v20, 1.0
	v_rcp_f32_e32 v22, v21
	s_mov_b64 s[4:5], -1
	v_fma_f32 v23, -v21, v22, 1.0
	v_fmac_f32_e32 v22, v23, v22
	v_div_scale_f32 v23, vcc, 1.0, v20, 1.0
	v_mul_f32_e32 v24, v23, v22
	v_fma_f32 v25, -v21, v24, v23
	v_fmac_f32_e32 v24, v25, v22
	v_fma_f32 v21, -v21, v24, v23
	v_div_fmas_f32 v21, v21, v22, v24
	v_div_fixup_f32 v36, v21, v20, 1.0
	ds_write_b32 v250, v36 offset:14336
	s_mov_b32 s73, s74
	s_branch .Lip_j7
.Lip_c7:
	v_mov_b32_e32 v36, v44
	s_mov_b64 s[4:5], -1
.Lip_j7:
	v_cvt_pk_bf16_f32 v20, v28, v29
	v_cvt_pk_bf16_f32 v21, v30, v31
	v_cvt_pk_bf16_f32 v22, v32, v33
	v_cvt_pk_bf16_f32 v23, v34, v35
	v_pk_mul_f32 v[18:19], v[18:19], v[36:37] op_sel_hi:[1,0]
	v_pk_mul_f32 v[16:17], v[16:17], v[36:37] op_sel_hi:[1,0]
	v_pk_mul_f32 v[14:15], v[14:15], v[36:37] op_sel_hi:[1,0]
	v_pk_mul_f32 v[12:13], v[12:13], v[36:37] op_sel_hi:[1,0]
	s_and_b64 vcc, exec, s[44:45]
	global_store_dwordx4 v[48:49], v[20:23], off offset:256
	s_cbranch_vccnz .LBB0_186
	v_mov_b64_e32 v[26:27], v[14:15]
	v_mov_b64_e32 v[22:23], v[18:19]
	s_and_b64 vcc, exec, s[42:43]
	v_mov_b64_e32 v[24:25], v[12:13]
	v_mov_b64_e32 v[20:21], v[16:17]
	s_cbranch_vccnz .LBB0_185
	v_pk_mul_f32 v[20:21], v[18:19], v[18:19]
	v_pk_mul_f32 v[22:23], v[16:17], v[16:17]
	s_mov_b32 s4, 0xf800000
	v_pk_mov_b32 v[24:25], v[22:23], v[20:21] op_sel:[1,0]
	v_mov_b32_e32 v23, v21
	v_pk_add_f32 v[20:21], v[24:25], v[22:23]
	v_pk_mul_f32 v[22:23], v[14:15], v[14:15]
	v_pk_mul_f32 v[24:25], v[12:13], v[12:13]
	v_mov_b32_e32 v26, v22
	v_mov_b32_e32 v27, v24
	v_mov_b32_e32 v24, v23
	v_pk_add_f32 v[22:23], v[26:27], v[24:25]
	v_add_f32_e32 v20, v20, v21
	v_add_f32_e32 v20, v23, v20
	v_add_f32_e32 v20, v22, v20
	v_and_b32_e32 v22, 64, v218
	v_xor_b32_e32 v21, 16, v218
	v_add_u32_e32 v22, 64, v22
	v_cmp_lt_i32_e32 vcc, v21, v22
	s_nop 1
	v_cndmask_b32_e32 v21, v218, v21, vcc
	v_lshlrev_b32_e32 v21, 2, v21
	ds_bpermute_b32 v21, v21, v20
	s_waitcnt lgkmcnt(0)
	v_add_f32_e32 v20, v20, v21
	v_xor_b32_e32 v21, 32, v218
	v_cmp_lt_i32_e32 vcc, v21, v22
	s_nop 1
	v_cndmask_b32_e32 v21, v218, v21, vcc
	v_lshlrev_b32_e32 v21, 2, v21
	ds_bpermute_b32 v21, v21, v20
	s_waitcnt lgkmcnt(0)
	v_add_f32_e32 v20, v20, v21
	v_fmamk_f32 v20, v20, 0x3d000000, v215
	v_mul_f32_e32 v21, 0x4f800000, v20
	v_cmp_gt_f32_e32 vcc, s4, v20
	s_nop 1
	v_cndmask_b32_e32 v20, v20, v21, vcc
	v_sqrt_f32_e32 v21, v20
	s_nop 0
	v_add_u32_e32 v22, -1, v21
	v_fma_f32 v23, -v22, v21, v20
	v_cmp_ge_f32_e64 s[4:5], 0, v23
	v_add_u32_e32 v23, 1, v21
	s_nop 0
	v_cndmask_b32_e64 v22, v21, v22, s[4:5]
	v_fma_f32 v21, -v23, v21, v20
	v_cmp_lt_f32_e64 s[4:5], 0, v21
	s_nop 1
	v_cndmask_b32_e64 v21, v22, v23, s[4:5]
	v_mul_f32_e32 v22, 0x37800000, v21
	v_cndmask_b32_e32 v21, v21, v22, vcc
	v_cmp_class_f32_e32 vcc, v20, v216
	s_nop 1
	v_cndmask_b32_e32 v20, v21, v20, vcc
	v_div_scale_f32 v21, s[4:5], v20, v20, 1.0
	v_rcp_f32_e32 v22, v21
	s_nop 0
	v_fma_f32 v23, -v21, v22, 1.0
	v_fmac_f32_e32 v22, v23, v22
	v_div_scale_f32 v23, vcc, 1.0, v20, 1.0
	v_mul_f32_e32 v24, v23, v22
	v_fma_f32 v25, -v21, v24, v23
	v_fmac_f32_e32 v24, v25, v22
	v_fma_f32 v21, -v21, v24, v23
	v_div_fmas_f32 v21, v21, v22, v24
	v_div_fixup_f32 v24, v21, v20, 1.0
	v_pk_mul_f32 v[20:21], v[16:17], v[24:25] op_sel_hi:[1,0]
	v_pk_mul_f32 v[22:23], v[18:19], v[24:25] op_sel_hi:[1,0]
	v_pk_mul_f32 v[28:29], v[12:13], v[24:25] op_sel_hi:[1,0]
	v_pk_mul_f32 v[24:25], v[14:15], v[24:25] op_sel_hi:[1,0]
	v_pk_mul_f32 v[22:23], v[192:193], v[22:23]
	v_pk_mul_f32 v[20:21], v[190:191], v[20:21]
	v_pk_mul_f32 v[26:27], v[188:189], v[24:25]
	v_pk_mul_f32 v[24:25], v[186:187], v[28:29]

.LBB0_866:
	v_lshl_add_u32 v176, s59, 8, v1
	v_ashrrev_i32_e32 v177, 31, v176
	v_lshlrev_b32_e32 v250, 2, v0
	v_add_u32_e32 v250, 0x20000, v250
	s_cmp_eq_u32 s59, s72
	s_cbranch_scc1 .Lsg_cached
	v_lshl_add_u64 v[132:133], v[176:177], 4, s[24:25]
	v_mov_b64_e32 v[192:193], v[132:133]
	global_load_dwordx4 v[132:135], v[132:133], off
	global_load_dwordx4 v[188:191], v[192:193], off offset:256
	global_load_dwordx4 v[210:213], v[192:193], off offset:512
	global_load_dwordx4 v[234:237], v[192:193], off offset:768
	global_load_dwordx4 v[238:241], v[192:193], off offset:2048
	global_load_dwordx4 v[242:245], v[192:193], off offset:2304
	global_load_dwordx4 v[246:249], v[192:193], off offset:2560
	s_mov_b32 s18, 0xf800000
	v_or_b32_e32 v166, 16, v176
	v_ashrrev_i32_e32 v167, 31, v166
	v_or_b32_e32 v162, 32, v176
	v_ashrrev_i32_e32 v163, 31, v162
	v_or_b32_e32 v156, 48, v176
	v_ashrrev_i32_e32 v157, 31, v156
	v_add_u32_e32 v178, 0x90, v176
	v_ashrrev_i32_e32 v179, 31, v178
	v_add_u32_e32 v180, 0xa0, v176
	v_ashrrev_i32_e32 v181, 31, v180
	v_add_u32_e32 v182, 0xb0, v176
	v_ashrrev_i32_e32 v183, 31, v182
	s_nop 0
	s_nop 0
	s_nop 0
	s_waitcnt vmcnt(6)
	v_mov_b32_e32 v152, v133
	v_mov_b32_e32 v153, v134
	v_mov_b32_e32 v133, v135
	v_pk_add_f32 v[132:133], v[152:153], v[132:133]
	s_nop 0
	v_add_f32_e32 v132, v132, v133
	v_fmamk_f32 v132, v132, 0x3a800000, v215
	v_cmp_gt_f32_e32 vcc, s18, v132
	v_mul_f32_e32 v133, 0x4f800000, v132
	s_nop 0
	v_cndmask_b32_e32 v132, v132, v133, vcc
	v_sqrt_f32_e32 v133, v132
	s_nop 0
	v_add_u32_e32 v134, -1, v133
	v_fma_f32 v135, -v134, v133, v132
	v_cmp_ge_f32_e64 s[4:5], 0, v135
	v_add_u32_e32 v135, 1, v133
	s_nop 0
	v_cndmask_b32_e64 v134, v133, v134, s[4:5]
	v_fma_f32 v133, -v135, v133, v132
	v_cmp_lt_f32_e64 s[4:5], 0, v133
	s_nop 1
	v_cndmask_b32_e64 v133, v134, v135, s[4:5]
	v_mul_f32_e32 v134, 0x37800000, v133
	v_cndmask_b32_e32 v133, v133, v134, vcc
	v_cmp_class_f32_e32 vcc, v132, v216
	s_nop 1
	v_cndmask_b32_e32 v132, v133, v132, vcc
	v_div_scale_f32 v133, s[4:5], v132, v132, 1.0
	v_rcp_f32_e32 v134, v133
	s_nop 0
	v_fma_f32 v135, -v133, v134, 1.0
	v_fmac_f32_e32 v134, v135, v134
	v_div_scale_f32 v135, vcc, 1.0, v132, 1.0
	v_mul_f32_e32 v146, v135, v134
	v_fma_f32 v148, -v133, v146, v135
	v_fmac_f32_e32 v146, v148, v134
	v_fma_f32 v133, -v133, v146, v135
	v_div_fmas_f32 v133, v133, v134, v146
	v_div_fixup_f32 v158, v133, v132, 1.0
	v_lshl_add_u64 v[132:133], v[166:167], 4, s[24:25]
	s_nop 0
	s_waitcnt vmcnt(5)
	v_mov_b64_e32 v[132:133], v[188:189]
	v_mov_b64_e32 v[134:135], v[190:191]
	global_load_dwordx4 v[188:191], v[192:193], off offset:2816
	v_mov_b32_e32 v152, v133
	v_mov_b32_e32 v153, v134
	v_mov_b32_e32 v133, v135
	v_pk_add_f32 v[132:133], v[152:153], v[132:133]
	s_nop 0
	v_add_f32_e32 v132, v132, v133
	v_fmamk_f32 v132, v132, 0x3a800000, v215
	v_cmp_gt_f32_e32 vcc, s18, v132
	v_mul_f32_e32 v133, 0x4f800000, v132
	s_nop 0
	v_cndmask_b32_e32 v132, v132, v133, vcc
	v_sqrt_f32_e32 v133, v132
	s_nop 0
	s_nop 0
	v_add_u32_e32 v134, -1, v133
	v_fma_f32 v135, -v134, v133, v132
	v_cmp_ge_f32_e64 s[4:5], 0, v135
	v_add_u32_e32 v135, 1, v133
	s_nop 0
	v_cndmask_b32_e64 v134, v133, v134, s[4:5]
	v_fma_f32 v133, -v135, v133, v132
	v_cmp_lt_f32_e64 s[4:5], 0, v133
	s_nop 0
	s_nop 0
	v_cndmask_b32_e64 v133, v134, v135, s[4:5]
	v_mul_f32_e32 v134, 0x37800000, v133
	v_cndmask_b32_e32 v133, v133, v134, vcc
	v_cmp_class_f32_e32 vcc, v132, v216
	s_nop 1
	v_cndmask_b32_e32 v132, v133, v132, vcc
	v_div_scale_f32 v133, s[4:5], v132, v132, 1.0
	v_rcp_f32_e32 v134, v133
	s_nop 0
	v_fma_f32 v135, -v133, v134, 1.0
	v_fmac_f32_e32 v134, v135, v134
	v_div_scale_f32 v135, vcc, 1.0, v132, 1.0
	v_mul_f32_e32 v146, v135, v134
	v_fma_f32 v148, -v133, v146, v135
	v_fmac_f32_e32 v146, v148, v134
	v_fma_f32 v133, -v133, v146, v135
	v_div_fmas_f32 v133, v133, v134, v146
	v_div_fixup_f32 v154, v133, v132, 1.0
	v_lshl_add_u64 v[132:133], v[162:163], 4, s[24:25]
	s_waitcnt vmcnt(5)
	v_mov_b64_e32 v[132:133], v[210:211]
	v_mov_b64_e32 v[134:135], v[212:213]
	v_mov_b32_e32 v152, v133
	v_mov_b32_e32 v153, v134
	v_mov_b32_e32 v133, v135
	v_pk_add_f32 v[132:133], v[152:153], v[132:133]
	s_nop 0
	v_add_f32_e32 v132, v132, v133
	v_fmamk_f32 v132, v132, 0x3a800000, v215
	v_cmp_gt_f32_e32 vcc, s18, v132
	v_mul_f32_e32 v133, 0x4f800000, v132
	s_nop 0
	v_cndmask_b32_e32 v132, v132, v133, vcc
	v_sqrt_f32_e32 v133, v132
	s_nop 0
	v_add_u32_e32 v134, -1, v133
	v_fma_f32 v135, -v134, v133, v132
	v_cmp_ge_f32_e64 s[4:5], 0, v135
	v_add_u32_e32 v135, 1, v133
	s_nop 0
	v_cndmask_b32_e64 v134, v133, v134, s[4:5]
	v_fma_f32 v133, -v135, v133, v132
	v_cmp_lt_f32_e64 s[4:5], 0, v133
	s_nop 1
	v_cndmask_b32_e64 v133, v134, v135, s[4:5]
	v_mul_f32_e32 v134, 0x37800000, v133
	v_cndmask_b32_e32 v133, v133, v134, vcc
	v_cmp_class_f32_e32 vcc, v132, v216
	s_nop 1
	v_cndmask_b32_e32 v132, v133, v132, vcc
	v_div_scale_f32 v133, s[4:5], v132, v132, 1.0
	v_rcp_f32_e32 v134, v133
	s_nop 0
	v_fma_f32 v135, -v133, v134, 1.0
	v_fmac_f32_e32 v134, v135, v134
	v_div_scale_f32 v135, vcc, 1.0, v132, 1.0
	v_mul_f32_e32 v146, v135, v134
	v_fma_f32 v148, -v133, v146, v135
	v_fmac_f32_e32 v146, v148, v134
	v_fma_f32 v133, -v133, v146, v135
	v_div_fmas_f32 v133, v133, v134, v146
	v_div_fixup_f32 v150, v133, v132, 1.0
	v_lshl_add_u64 v[132:133], v[156:157], 4, s[24:25]
	s_waitcnt vmcnt(4)
	v_mov_b64_e32 v[132:133], v[234:235]
	v_mov_b64_e32 v[134:135], v[236:237]
	v_mov_b32_e32 v152, v133
	v_mov_b32_e32 v153, v134
	v_mov_b32_e32 v133, v135
	v_pk_add_f32 v[132:133], v[152:153], v[132:133]
	v_add_u32_e32 v152, 0x80, v176
	v_add_f32_e32 v132, v132, v133
	v_fmamk_f32 v132, v132, 0x3a800000, v215
	v_cmp_gt_f32_e32 vcc, s18, v132
	v_mul_f32_e32 v133, 0x4f800000, v132
	v_ashrrev_i32_e32 v153, 31, v152
	v_cndmask_b32_e32 v132, v132, v133, vcc
	v_sqrt_f32_e32 v133, v132
	s_nop 0
	v_add_u32_e32 v134, -1, v133
	v_fma_f32 v135, -v134, v133, v132
	v_cmp_ge_f32_e64 s[4:5], 0, v135
	v_add_u32_e32 v135, 1, v133
	s_nop 0
	v_cndmask_b32_e64 v134, v133, v134, s[4:5]
	v_fma_f32 v133, -v135, v133, v132
	v_cmp_lt_f32_e64 s[4:5], 0, v133
	s_nop 1
	v_cndmask_b32_e64 v133, v134, v135, s[4:5]
	v_mul_f32_e32 v134, 0x37800000, v133
	v_cndmask_b32_e32 v133, v133, v134, vcc
	v_cmp_class_f32_e32 vcc, v132, v216
	s_nop 1
	v_cndmask_b32_e32 v132, v133, v132, vcc
	v_div_scale_f32 v133, s[4:5], v132, v132, 1.0
	v_rcp_f32_e32 v134, v133
	s_nop 0
	v_fma_f32 v135, -v133, v134, 1.0
	v_fmac_f32_e32 v134, v135, v134
	v_div_scale_f32 v135, vcc, 1.0, v132, 1.0
	v_mul_f32_e32 v146, v135, v134
	v_fma_f32 v148, -v133, v146, v135
	v_fmac_f32_e32 v146, v148, v134
	v_fma_f32 v133, -v133, v146, v135
	v_div_fmas_f32 v133, v133, v134, v146
	v_div_fixup_f32 v148, v133, v132, 1.0
	v_lshl_add_u64 v[132:133], v[152:153], 4, s[24:25]
	s_waitcnt vmcnt(3)
	v_mov_b64_e32 v[132:133], v[238:239]
	v_mov_b64_e32 v[134:135], v[240:241]
	v_mov_b32_e32 v160, v133
	v_mov_b32_e32 v161, v134
	v_mov_b32_e32 v133, v135
	v_pk_add_f32 v[132:133], v[160:161], v[132:133]
	s_nop 0
	v_add_f32_e32 v132, v132, v133
	v_fmamk_f32 v132, v132, 0x3a800000, v215
	v_cmp_gt_f32_e32 vcc, s18, v132
	v_mul_f32_e32 v133, 0x4f800000, v132
	s_nop 0
	v_cndmask_b32_e32 v132, v132, v133, vcc
	v_sqrt_f32_e32 v133, v132
	s_nop 0
	v_add_u32_e32 v134, -1, v133
	v_fma_f32 v135, -v134, v133, v132
	v_cmp_ge_f32_e64 s[4:5], 0, v135
	v_add_u32_e32 v135, 1, v133
	s_nop 0
	v_cndmask_b32_e64 v134, v133, v134, s[4:5]
	v_fma_f32 v133, -v135, v133, v132
	v_cmp_lt_f32_e64 s[4:5], 0, v133
	s_nop 1
	v_cndmask_b32_e64 v133, v134, v135, s[4:5]
	v_mul_f32_e32 v134, 0x37800000, v133
	v_cndmask_b32_e32 v133, v133, v134, vcc
	v_cmp_class_f32_e32 vcc, v132, v216
	s_nop 1
	v_cndmask_b32_e32 v132, v133, v132, vcc
	v_div_scale_f32 v133, s[4:5], v132, v132, 1.0
	v_rcp_f32_e32 v134, v133
	s_nop 0
	v_fma_f32 v135, -v133, v134, 1.0
	v_fmac_f32_e32 v134, v135, v134
	v_div_scale_f32 v135, vcc, 1.0, v132, 1.0
	v_mul_f32_e32 v146, v135, v134
	v_fma_f32 v153, -v133, v146, v135
	v_fmac_f32_e32 v146, v153, v134
	v_fma_f32 v133, -v133, v146, v135
	v_div_fmas_f32 v133, v133, v134, v146
	v_div_fixup_f32 v146, v133, v132, 1.0
	v_lshl_add_u64 v[132:133], v[178:179], 4, s[24:25]
	s_waitcnt vmcnt(2)
	v_mov_b64_e32 v[132:133], v[242:243]
	v_mov_b64_e32 v[134:135], v[244:245]
	v_mov_b32_e32 v160, v133
	v_mov_b32_e32 v161, v134
	v_mov_b32_e32 v133, v135
	v_pk_add_f32 v[132:133], v[160:161], v[132:133]
	s_nop 0
	v_add_f32_e32 v132, v132, v133
	v_fmamk_f32 v132, v132, 0x3a800000, v215
	v_cmp_gt_f32_e32 vcc, s18, v132
	v_mul_f32_e32 v133, 0x4f800000, v132
	s_nop 0
	v_cndmask_b32_e32 v132, v132, v133, vcc
	v_sqrt_f32_e32 v133, v132
	s_nop 0
	v_add_u32_e32 v134, -1, v133
	v_fma_f32 v135, -v134, v133, v132
	v_cmp_ge_f32_e64 s[4:5], 0, v135
	v_add_u32_e32 v135, 1, v133
	s_nop 0
	v_cndmask_b32_e64 v134, v133, v134, s[4:5]
	v_fma_f32 v133, -v135, v133, v132
	v_cmp_lt_f32_e64 s[4:5], 0, v133
	s_nop 1
	v_cndmask_b32_e64 v133, v134, v135, s[4:5]
	v_mul_f32_e32 v134, 0x37800000, v133
	v_cndmask_b32_e32 v133, v133, v134, vcc
	v_cmp_class_f32_e32 vcc, v132, v216
	s_nop 1
	v_cndmask_b32_e32 v132, v133, v132, vcc
	v_div_scale_f32 v133, s[4:5], v132, v132, 1.0
	v_rcp_f32_e32 v134, v133
	s_nop 0
	v_fma_f32 v135, -v133, v134, 1.0
	v_fmac_f32_e32 v134, v135, v134
	v_div_scale_f32 v135, vcc, 1.0, v132, 1.0
	v_mul_f32_e32 v153, v135, v134
	v_fma_f32 v155, -v133, v153, v135
	v_fmac_f32_e32 v153, v155, v134
	v_fma_f32 v133, -v133, v153, v135
	v_div_fmas_f32 v133, v133, v134, v153
	v_div_fixup_f32 v160, v133, v132, 1.0
	v_lshl_add_u64 v[132:133], v[180:181], 4, s[24:25]
	s_waitcnt vmcnt(1)
	v_mov_b64_e32 v[132:133], v[246:247]
	v_mov_b64_e32 v[134:135], v[248:249]
	v_mov_b32_e32 v164, v133
	v_mov_b32_e32 v165, v134
	v_mov_b32_e32 v133, v135
	v_pk_add_f32 v[132:133], v[164:165], v[132:133]
	s_nop 0
	v_add_f32_e32 v132, v132, v133
	v_fmamk_f32 v132, v132, 0x3a800000, v215
	v_cmp_gt_f32_e32 vcc, s18, v132
	v_mul_f32_e32 v133, 0x4f800000, v132
	s_nop 0
	v_cndmask_b32_e32 v132, v132, v133, vcc
	v_sqrt_f32_e32 v133, v132
	s_nop 0
	v_add_u32_e32 v134, -1, v133
	v_fma_f32 v135, -v134, v133, v132
	v_cmp_ge_f32_e64 s[4:5], 0, v135
	v_add_u32_e32 v135, 1, v133
	s_nop 0
	v_cndmask_b32_e64 v134, v133, v134, s[4:5]
	v_fma_f32 v133, -v135, v133, v132
	v_cmp_lt_f32_e64 s[4:5], 0, v133
	s_nop 1
	v_cndmask_b32_e64 v133, v134, v135, s[4:5]
	v_mul_f32_e32 v134, 0x37800000, v133
	v_cndmask_b32_e32 v133, v133, v134, vcc
	v_cmp_class_f32_e32 vcc, v132, v216
	s_nop 1
	v_cndmask_b32_e32 v132, v133, v132, vcc
	v_div_scale_f32 v133, s[4:5], v132, v132, 1.0
	v_rcp_f32_e32 v134, v133
	s_nop 0
	v_fma_f32 v135, -v133, v134, 1.0
	v_fmac_f32_e32 v134, v135, v134
	v_div_scale_f32 v135, vcc, 1.0, v132, 1.0
	v_mul_f32_e32 v153, v135, v134
	v_fma_f32 v155, -v133, v153, v135
	v_fmac_f32_e32 v153, v155, v134
	v_fma_f32 v133, -v133, v153, v135
	v_div_fmas_f32 v133, v133, v134, v153
	v_div_fixup_f32 v164, v133, v132, 1.0
	v_lshl_add_u64 v[132:133], v[182:183], 4, s[24:25]
	s_waitcnt vmcnt(0)
	v_mov_b64_e32 v[132:133], v[188:189]
	v_mov_b64_e32 v[134:135], v[190:191]
	v_mov_b32_e32 v184, v133
	v_mov_b32_e32 v185, v134
	v_mov_b32_e32 v133, v135
	v_pk_add_f32 v[132:133], v[184:185], v[132:133]
	v_lshl_or_b32 v184, s58, 7, v149
	v_add_f32_e32 v132, v132, v133
	v_fmamk_f32 v132, v132, 0x3a800000, v215
	v_cmp_gt_f32_e32 vcc, s18, v132
	v_mul_f32_e32 v133, 0x4f800000, v132
	v_ashrrev_i32_e32 v185, 31, v184
	v_cndmask_b32_e32 v132, v132, v133, vcc
	v_sqrt_f32_e32 v133, v132
	s_movk_i32 s18, 0x1600
	v_add_u32_e32 v134, -1, v133
	v_fma_f32 v135, -v134, v133, v132
	v_cmp_ge_f32_e64 s[4:5], 0, v135
	v_add_u32_e32 v135, 1, v133
	s_nop 0
	v_cndmask_b32_e64 v134, v133, v134, s[4:5]
	v_fma_f32 v133, -v135, v133, v132
	v_cmp_lt_f32_e64 s[4:5], 0, v133
	s_nop 1
	v_cndmask_b32_e64 v133, v134, v135, s[4:5]
	v_mul_f32_e32 v134, 0x37800000, v133
	v_cndmask_b32_e32 v133, v133, v134, vcc
	v_cmp_class_f32_e32 vcc, v132, v216
	s_nop 1
	v_cndmask_b32_e32 v132, v133, v132, vcc
	v_div_scale_f32 v133, s[4:5], v132, v132, 1.0
	v_rcp_f32_e32 v134, v133
	s_nop 0
	v_fma_f32 v135, -v133, v134, 1.0
	v_fmac_f32_e32 v134, v135, v134
	v_div_scale_f32 v135, vcc, 1.0, v132, 1.0
	v_mul_f32_e32 v153, v135, v134
	v_fma_f32 v155, -v133, v153, v135
	v_fmac_f32_e32 v153, v155, v134
	v_fma_f32 v133, -v133, v153, v135
	v_div_fmas_f32 v133, v133, v134, v153
	v_div_fixup_f32 v132, v133, v132, 1.0
	ds_write_b32 v250, v158
	ds_write_b32 v250, v154 offset:2048
	ds_write_b32 v250, v150 offset:4096
	ds_write_b32 v250, v148 offset:6144
	ds_write_b32 v250, v146 offset:8192
	ds_write_b32 v250, v160 offset:10240
	ds_write_b32 v250, v164 offset:12288
	ds_write_b32 v250, v132 offset:14336
	s_mov_b32 s72, s59
	s_branch .Lsg_join
.Lsg_cached:
	ds_read_b32 v158, v250
	ds_read_b32 v154, v250 offset:2048
	ds_read_b32 v150, v250 offset:4096
	ds_read_b32 v148, v250 offset:6144
	ds_read_b32 v146, v250 offset:8192
	ds_read_b32 v160, v250 offset:10240
	ds_read_b32 v164, v250 offset:12288
	ds_read_b32 v132, v250 offset:14336
	v_lshl_or_b32 v184, s58, 7, v149
	v_ashrrev_i32_e32 v185, 31, v184
	s_waitcnt lgkmcnt(0)
.Lsg_join:
	s_mov_b32 s74, 0xbfb8aa3b
	s_mov_b32 s75, 0xbfb8aa3b
	s_mov_b32 s80, 1.0
	s_mov_b32 s81, 1.0
	s_mov_b32 s76, 0x16000
	s_mov_b32 s77, 0
	s_mov_b32 s78, 0x6e000
	s_mov_b32 s79, 0
	s_movk_i32 s18, 0x1600
	v_mov_b64_e32 v[242:243], s[22:23]
	v_lshlrev_b64 v[244:245], 1, v[184:185]
	v_mad_i64_i32 v[242:243], s[4:5], v176, s18, v[242:243]
	s_nop 0
	v_lshl_add_u64 v[242:243], v[242:243], 0, v[244:245]
	v_pk_mul_f32 v[128:129], v[128:129], v[158:159] op_sel_hi:[1,0]
	v_pk_mul_f32 v[130:131], v[130:131], v[158:159] op_sel_hi:[1,0]
	v_pk_mul_f32 v[124:125], v[124:125], v[158:159] op_sel_hi:[1,0]
	v_pk_mul_f32 v[126:127], v[126:127], v[158:159] op_sel_hi:[1,0]
	v_pk_mul_f32 v[120:121], v[120:121], v[158:159] op_sel_hi:[1,0]
	v_pk_mul_f32 v[122:123], v[122:123], v[158:159] op_sel_hi:[1,0]
	v_pk_mul_f32 v[116:117], v[116:117], v[158:159] op_sel_hi:[1,0]
	v_pk_mul_f32 v[118:119], v[118:119], v[158:159] op_sel_hi:[1,0]
	v_pk_mul_f32 v[234:235], v[128:129], s[74:75]
	v_pk_mul_f32 v[236:237], v[130:131], s[74:75]
	v_pk_mul_f32 v[238:239], v[124:125], s[74:75]
	v_pk_mul_f32 v[240:241], v[126:127], s[74:75]
	v_exp_f32_e32 v234, v234
	v_exp_f32_e32 v235, v235
	v_exp_f32_e32 v236, v236
	v_exp_f32_e32 v237, v237
	v_exp_f32_e32 v238, v238
	v_exp_f32_e32 v239, v239
	v_exp_f32_e32 v240, v240
	v_exp_f32_e32 v241, v241
	v_lshl_add_u64 v[244:245], v[242:243], 0, s[76:77]
	v_pk_add_f32 v[234:235], v[234:235], s[80:81]
	v_pk_add_f32 v[236:237], v[236:237], s[80:81]
	v_pk_add_f32 v[238:239], v[238:239], s[80:81]
	v_pk_add_f32 v[240:241], v[240:241], s[80:81]
	v_rcp_f32_e32 v234, v234
	v_rcp_f32_e32 v235, v235
	v_rcp_f32_e32 v236, v236
	v_rcp_f32_e32 v237, v237
	v_rcp_f32_e32 v238, v238
	v_rcp_f32_e32 v239, v239
	v_rcp_f32_e32 v240, v240
	v_rcp_f32_e32 v241, v241
	s_nop 0
	v_pk_mul_f32 v[128:129], v[128:129], v[234:235]
	v_pk_mul_f32 v[130:131], v[130:131], v[236:237]
	v_pk_mul_f32 v[124:125], v[124:125], v[238:239]
	v_pk_mul_f32 v[126:127], v[126:127], v[240:241]
	v_pk_mul_f32 v[128:129], v[120:121], v[128:129]
	v_pk_mul_f32 v[130:131], v[122:123], v[130:131]
	v_pk_mul_f32 v[124:125], v[116:117], v[124:125]
	v_pk_mul_f32 v[126:127], v[118:119], v[126:127]
	v_cvt_pk_bf16_f32 v246, v128, v129
	v_cvt_pk_bf16_f32 v247, v130, v131
	v_cvt_pk_bf16_f32 v248, v124, v125
	v_cvt_pk_bf16_f32 v249, v126, v127
	global_store_dwordx4 v[242:243], v[246:249], off
	v_pk_mul_f32 v[112:113], v[112:113], v[154:155] op_sel_hi:[1,0]
	v_pk_mul_f32 v[114:115], v[114:115], v[154:155] op_sel_hi:[1,0]
	v_pk_mul_f32 v[108:109], v[108:109], v[154:155] op_sel_hi:[1,0]
	v_pk_mul_f32 v[110:111], v[110:111], v[154:155] op_sel_hi:[1,0]
	v_pk_mul_f32 v[104:105], v[104:105], v[154:155] op_sel_hi:[1,0]
	v_pk_mul_f32 v[106:107], v[106:107], v[154:155] op_sel_hi:[1,0]
	v_pk_mul_f32 v[100:101], v[100:101], v[154:155] op_sel_hi:[1,0]
	v_pk_mul_f32 v[102:103], v[102:103], v[154:155] op_sel_hi:[1,0]
	v_pk_mul_f32 v[234:235], v[112:113], s[74:75]
	v_pk_mul_f32 v[236:237], v[114:115], s[74:75]
	v_pk_mul_f32 v[238:239], v[108:109], s[74:75]
	v_pk_mul_f32 v[240:241], v[110:111], s[74:75]
	v_exp_f32_e32 v234, v234
	v_exp_f32_e32 v235, v235
	v_exp_f32_e32 v236, v236
	v_exp_f32_e32 v237, v237
	v_exp_f32_e32 v238, v238
	v_exp_f32_e32 v239, v239
	v_exp_f32_e32 v240, v240
	v_exp_f32_e32 v241, v241
	v_lshl_add_u64 v[242:243], v[244:245], 0, s[76:77]
	v_pk_add_f32 v[234:235], v[234:235], s[80:81]
	v_pk_add_f32 v[236:237], v[236:237], s[80:81]
	v_pk_add_f32 v[238:239], v[238:239], s[80:81]
	v_pk_add_f32 v[240:241], v[240:241], s[80:81]
	v_rcp_f32_e32 v234, v234
	v_rcp_f32_e32 v235, v235
	v_rcp_f32_e32 v236, v236
	v_rcp_f32_e32 v237, v237
	v_rcp_f32_e32 v238, v238
	v_rcp_f32_e32 v239, v239
	v_rcp_f32_e32 v240, v240
	v_rcp_f32_e32 v241, v241
	s_nop 0
	v_pk_mul_f32 v[112:113], v[112:113], v[234:235]
	v_pk_mul_f32 v[114:115], v[114:115], v[236:237]
	v_pk_mul_f32 v[108:109], v[108:109], v[238:239]
	v_pk_mul_f32 v[110:111], v[110:111], v[240:241]
	v_pk_mul_f32 v[112:113], v[104:105], v[112:113]
	v_pk_mul_f32 v[114:115], v[106:107], v[114:115]
	v_pk_mul_f32 v[108:109], v[100:101], v[108:109]
	v_pk_mul_f32 v[110:111], v[102:103], v[110:111]
	v_cvt_pk_bf16_f32 v246, v112, v113
	v_cvt_pk_bf16_f32 v247, v114, v115
	v_cvt_pk_bf16_f32 v248, v108, v109
	v_cvt_pk_bf16_f32 v249, v110, v111
	global_store_dwordx4 v[244:245], v[246:249], off
	v_pk_mul_f32 v[96:97], v[96:97], v[150:151] op_sel_hi:[1,0]
	v_pk_mul_f32 v[98:99], v[98:99], v[150:151] op_sel_hi:[1,0]
	v_pk_mul_f32 v[92:93], v[92:93], v[150:151] op_sel_hi:[1,0]
	v_pk_mul_f32 v[94:95], v[94:95], v[150:151] op_sel_hi:[1,0]
	v_pk_mul_f32 v[88:89], v[88:89], v[150:151] op_sel_hi:[1,0]
	v_pk_mul_f32 v[90:91], v[90:91], v[150:151] op_sel_hi:[1,0]
	v_pk_mul_f32 v[84:85], v[84:85], v[150:151] op_sel_hi:[1,0]
	v_pk_mul_f32 v[86:87], v[86:87], v[150:151] op_sel_hi:[1,0]
	v_pk_mul_f32 v[234:235], v[96:97], s[74:75]
	v_pk_mul_f32 v[236:237], v[98:99], s[74:75]
	v_pk_mul_f32 v[238:239], v[92:93], s[74:75]
	v_pk_mul_f32 v[240:241], v[94:95], s[74:75]
	v_exp_f32_e32 v234, v234
	v_exp_f32_e32 v235, v235
	v_exp_f32_e32 v236, v236
	v_exp_f32_e32 v237, v237
	v_exp_f32_e32 v238, v238
	v_exp_f32_e32 v239, v239
	v_exp_f32_e32 v240, v240
	v_exp_f32_e32 v241, v241
	v_lshl_add_u64 v[244:245], v[242:243], 0, s[76:77]
	v_pk_add_f32 v[234:235], v[234:235], s[80:81]
	v_pk_add_f32 v[236:237], v[236:237], s[80:81]
	v_pk_add_f32 v[238:239], v[238:239], s[80:81]
	v_pk_add_f32 v[240:241], v[240:241], s[80:81]
	v_rcp_f32_e32 v234, v234
	v_rcp_f32_e32 v235, v235
	v_rcp_f32_e32 v236, v236
	v_rcp_f32_e32 v237, v237
	v_rcp_f32_e32 v238, v238
	v_rcp_f32_e32 v239, v239
	v_rcp_f32_e32 v240, v240
	v_rcp_f32_e32 v241, v241
	s_nop 0
	v_pk_mul_f32 v[96:97], v[96:97], v[234:235]
	v_pk_mul_f32 v[98:99], v[98:99], v[236:237]
	v_pk_mul_f32 v[92:93], v[92:93], v[238:239]
	v_pk_mul_f32 v[94:95], v[94:95], v[240:241]
	v_pk_mul_f32 v[96:97], v[88:89], v[96:97]
	v_pk_mul_f32 v[98:99], v[90:91], v[98:99]
	v_pk_mul_f32 v[92:93], v[84:85], v[92:93]
	v_pk_mul_f32 v[94:95], v[86:87], v[94:95]
	v_cvt_pk_bf16_f32 v246, v96, v97
	v_cvt_pk_bf16_f32 v247, v98, v99
	v_cvt_pk_bf16_f32 v248, v92, v93
	v_cvt_pk_bf16_f32 v249, v94, v95
	global_store_dwordx4 v[242:243], v[246:249], off
	v_pk_mul_f32 v[80:81], v[80:81], v[148:149] op_sel_hi:[1,0]
	v_pk_mul_f32 v[82:83], v[82:83], v[148:149] op_sel_hi:[1,0]
	v_pk_mul_f32 v[76:77], v[76:77], v[148:149] op_sel_hi:[1,0]
	v_pk_mul_f32 v[78:79], v[78:79], v[148:149] op_sel_hi:[1,0]
	v_pk_mul_f32 v[72:73], v[72:73], v[148:149] op_sel_hi:[1,0]
	v_pk_mul_f32 v[74:75], v[74:75], v[148:149] op_sel_hi:[1,0]
	v_pk_mul_f32 v[68:69], v[68:69], v[148:149] op_sel_hi:[1,0]
	v_pk_mul_f32 v[70:71], v[70:71], v[148:149] op_sel_hi:[1,0]
	v_pk_mul_f32 v[234:235], v[80:81], s[74:75]
	v_pk_mul_f32 v[236:237], v[82:83], s[74:75]
	v_pk_mul_f32 v[238:239], v[76:77], s[74:75]
	v_pk_mul_f32 v[240:241], v[78:79], s[74:75]
	v_exp_f32_e32 v234, v234
	v_exp_f32_e32 v235, v235
	v_exp_f32_e32 v236, v236
	v_exp_f32_e32 v237, v237
	v_exp_f32_e32 v238, v238
	v_exp_f32_e32 v239, v239
	v_exp_f32_e32 v240, v240
	v_exp_f32_e32 v241, v241
	v_lshl_add_u64 v[242:243], v[244:245], 0, s[78:79]
	v_pk_add_f32 v[234:235], v[234:235], s[80:81]
	v_pk_add_f32 v[236:237], v[236:237], s[80:81]
	v_pk_add_f32 v[238:239], v[238:239], s[80:81]
	v_pk_add_f32 v[240:241], v[240:241], s[80:81]
	v_rcp_f32_e32 v234, v234
	v_rcp_f32_e32 v235, v235
	v_rcp_f32_e32 v236, v236
	v_rcp_f32_e32 v237, v237
	v_rcp_f32_e32 v238, v238
	v_rcp_f32_e32 v239, v239
	v_rcp_f32_e32 v240, v240
	v_rcp_f32_e32 v241, v241
	s_nop 0
	v_pk_mul_f32 v[80:81], v[80:81], v[234:235]
	v_pk_mul_f32 v[82:83], v[82:83], v[236:237]
	v_pk_mul_f32 v[76:77], v[76:77], v[238:239]
	v_pk_mul_f32 v[78:79], v[78:79], v[240:241]
	v_pk_mul_f32 v[80:81], v[72:73], v[80:81]
	v_pk_mul_f32 v[82:83], v[74:75], v[82:83]
	v_pk_mul_f32 v[76:77], v[68:69], v[76:77]
	v_pk_mul_f32 v[78:79], v[70:71], v[78:79]
	v_cvt_pk_bf16_f32 v246, v80, v81
	v_cvt_pk_bf16_f32 v247, v82, v83
	v_cvt_pk_bf16_f32 v248, v76, v77
	v_cvt_pk_bf16_f32 v249, v78, v79
	global_store_dwordx4 v[244:245], v[246:249], off
	v_pk_mul_f32 v[64:65], v[64:65], v[146:147] op_sel_hi:[1,0]
	v_pk_mul_f32 v[66:67], v[66:67], v[146:147] op_sel_hi:[1,0]
	v_pk_mul_f32 v[60:61], v[60:61], v[146:147] op_sel_hi:[1,0]
	v_pk_mul_f32 v[62:63], v[62:63], v[146:147] op_sel_hi:[1,0]
	v_pk_mul_f32 v[56:57], v[56:57], v[146:147] op_sel_hi:[1,0]
	v_pk_mul_f32 v[58:59], v[58:59], v[146:147] op_sel_hi:[1,0]
	v_pk_mul_f32 v[52:53], v[52:53], v[146:147] op_sel_hi:[1,0]
	v_pk_mul_f32 v[54:55], v[54:55], v[146:147] op_sel_hi:[1,0]
	v_pk_mul_f32 v[234:235], v[64:65], s[74:75]
	v_pk_mul_f32 v[236:237], v[66:67], s[74:75]
	v_pk_mul_f32 v[238:239], v[60:61], s[74:75]
	v_pk_mul_f32 v[240:241], v[62:63], s[74:75]
	v_exp_f32_e32 v234, v234
	v_exp_f32_e32 v235, v235
	v_exp_f32_e32 v236, v236
	v_exp_f32_e32 v237, v237
	v_exp_f32_e32 v238, v238
	v_exp_f32_e32 v239, v239
	v_exp_f32_e32 v240, v240
	v_exp_f32_e32 v241, v241
	v_lshl_add_u64 v[244:245], v[242:243], 0, s[76:77]
	v_pk_add_f32 v[234:235], v[234:235], s[80:81]
	v_pk_add_f32 v[236:237], v[236:237], s[80:81]
	v_pk_add_f32 v[238:239], v[238:239], s[80:81]
	v_pk_add_f32 v[240:241], v[240:241], s[80:81]
	v_rcp_f32_e32 v234, v234
	v_rcp_f32_e32 v235, v235
	v_rcp_f32_e32 v236, v236
	v_rcp_f32_e32 v237, v237
	v_rcp_f32_e32 v238, v238
	v_rcp_f32_e32 v239, v239
	v_rcp_f32_e32 v240, v240
	v_rcp_f32_e32 v241, v241
	s_nop 0
	v_pk_mul_f32 v[64:65], v[64:65], v[234:235]
	v_pk_mul_f32 v[66:67], v[66:67], v[236:237]
	v_pk_mul_f32 v[60:61], v[60:61], v[238:239]
	v_pk_mul_f32 v[62:63], v[62:63], v[240:241]
	v_pk_mul_f32 v[64:65], v[56:57], v[64:65]
	v_pk_mul_f32 v[66:67], v[58:59], v[66:67]
	v_pk_mul_f32 v[60:61], v[52:53], v[60:61]
	v_pk_mul_f32 v[62:63], v[54:55], v[62:63]
	v_cvt_pk_bf16_f32 v246, v64, v65
	v_cvt_pk_bf16_f32 v247, v66, v67
	v_cvt_pk_bf16_f32 v248, v60, v61
	v_cvt_pk_bf16_f32 v249, v62, v63
	global_store_dwordx4 v[242:243], v[246:249], off
	v_pk_mul_f32 v[48:49], v[48:49], v[160:161] op_sel_hi:[1,0]
	v_pk_mul_f32 v[50:51], v[50:51], v[160:161] op_sel_hi:[1,0]
	v_pk_mul_f32 v[44:45], v[44:45], v[160:161] op_sel_hi:[1,0]
	v_pk_mul_f32 v[46:47], v[46:47], v[160:161] op_sel_hi:[1,0]
	v_pk_mul_f32 v[40:41], v[40:41], v[160:161] op_sel_hi:[1,0]
	v_pk_mul_f32 v[42:43], v[42:43], v[160:161] op_sel_hi:[1,0]
	v_pk_mul_f32 v[36:37], v[36:37], v[160:161] op_sel_hi:[1,0]
	v_pk_mul_f32 v[38:39], v[38:39], v[160:161] op_sel_hi:[1,0]
	v_pk_mul_f32 v[234:235], v[48:49], s[74:75]
	v_pk_mul_f32 v[236:237], v[50:51], s[74:75]
	v_pk_mul_f32 v[238:239], v[44:45], s[74:75]
	v_pk_mul_f32 v[240:241], v[46:47], s[74:75]
	v_exp_f32_e32 v234, v234
	v_exp_f32_e32 v235, v235
	v_exp_f32_e32 v236, v236
	v_exp_f32_e32 v237, v237
	v_exp_f32_e32 v238, v238
	v_exp_f32_e32 v239, v239
	v_exp_f32_e32 v240, v240
	v_exp_f32_e32 v241, v241
	v_lshl_add_u64 v[242:243], v[244:245], 0, s[76:77]
	v_pk_add_f32 v[234:235], v[234:235], s[80:81]
	v_pk_add_f32 v[236:237], v[236:237], s[80:81]
	v_pk_add_f32 v[238:239], v[238:239], s[80:81]
	v_pk_add_f32 v[240:241], v[240:241], s[80:81]
	v_rcp_f32_e32 v234, v234
	v_rcp_f32_e32 v235, v235
	v_rcp_f32_e32 v236, v236
	v_rcp_f32_e32 v237, v237
	v_rcp_f32_e32 v238, v238
	v_rcp_f32_e32 v239, v239
	v_rcp_f32_e32 v240, v240
	v_rcp_f32_e32 v241, v241
	s_nop 0
	v_pk_mul_f32 v[48:49], v[48:49], v[234:235]
	v_pk_mul_f32 v[50:51], v[50:51], v[236:237]
	v_pk_mul_f32 v[44:45], v[44:45], v[238:239]
	v_pk_mul_f32 v[46:47], v[46:47], v[240:241]
	v_pk_mul_f32 v[48:49], v[40:41], v[48:49]
	v_pk_mul_f32 v[50:51], v[42:43], v[50:51]
	v_pk_mul_f32 v[44:45], v[36:37], v[44:45]
	v_pk_mul_f32 v[46:47], v[38:39], v[46:47]
	v_cvt_pk_bf16_f32 v246, v48, v49
	v_cvt_pk_bf16_f32 v247, v50, v51
	v_cvt_pk_bf16_f32 v248, v44, v45
	v_cvt_pk_bf16_f32 v249, v46, v47
	global_store_dwordx4 v[244:245], v[246:249], off
	v_pk_mul_f32 v[32:33], v[32:33], v[164:165] op_sel_hi:[1,0]
	v_pk_mul_f32 v[34:35], v[34:35], v[164:165] op_sel_hi:[1,0]
	v_pk_mul_f32 v[28:29], v[28:29], v[164:165] op_sel_hi:[1,0]
	v_pk_mul_f32 v[30:31], v[30:31], v[164:165] op_sel_hi:[1,0]
	v_pk_mul_f32 v[24:25], v[24:25], v[164:165] op_sel_hi:[1,0]
	v_pk_mul_f32 v[26:27], v[26:27], v[164:165] op_sel_hi:[1,0]
	v_pk_mul_f32 v[20:21], v[20:21], v[164:165] op_sel_hi:[1,0]
	v_pk_mul_f32 v[22:23], v[22:23], v[164:165] op_sel_hi:[1,0]
	v_pk_mul_f32 v[234:235], v[32:33], s[74:75]
	v_pk_mul_f32 v[236:237], v[34:35], s[74:75]
	v_pk_mul_f32 v[238:239], v[28:29], s[74:75]
	v_pk_mul_f32 v[240:241], v[30:31], s[74:75]
	v_exp_f32_e32 v234, v234
	v_exp_f32_e32 v235, v235
	v_exp_f32_e32 v236, v236
	v_exp_f32_e32 v237, v237
	v_exp_f32_e32 v238, v238
	v_exp_f32_e32 v239, v239
	v_exp_f32_e32 v240, v240
	v_exp_f32_e32 v241, v241
	v_lshl_add_u64 v[244:245], v[242:243], 0, s[76:77]
	v_pk_add_f32 v[234:235], v[234:235], s[80:81]
	v_pk_add_f32 v[236:237], v[236:237], s[80:81]
	v_pk_add_f32 v[238:239], v[238:239], s[80:81]
	v_pk_add_f32 v[240:241], v[240:241], s[80:81]
	v_rcp_f32_e32 v234, v234
	v_rcp_f32_e32 v235, v235
	v_rcp_f32_e32 v236, v236
	v_rcp_f32_e32 v237, v237
	v_rcp_f32_e32 v238, v238
	v_rcp_f32_e32 v239, v239
	v_rcp_f32_e32 v240, v240
	v_rcp_f32_e32 v241, v241
	s_nop 0
	v_pk_mul_f32 v[32:33], v[32:33], v[234:235]
	v_pk_mul_f32 v[34:35], v[34:35], v[236:237]
	v_pk_mul_f32 v[28:29], v[28:29], v[238:239]
	v_pk_mul_f32 v[30:31], v[30:31], v[240:241]
	v_pk_mul_f32 v[32:33], v[24:25], v[32:33]
	v_pk_mul_f32 v[34:35], v[26:27], v[34:35]
	v_pk_mul_f32 v[28:29], v[20:21], v[28:29]
	v_pk_mul_f32 v[30:31], v[22:23], v[30:31]
	v_cvt_pk_bf16_f32 v246, v32, v33
	v_cvt_pk_bf16_f32 v247, v34, v35
	v_cvt_pk_bf16_f32 v248, v28, v29
	v_cvt_pk_bf16_f32 v249, v30, v31
	global_store_dwordx4 v[242:243], v[246:249], off
	v_pk_mul_f32 v[16:17], v[16:17], v[132:133] op_sel_hi:[1,0]
	v_pk_mul_f32 v[18:19], v[18:19], v[132:133] op_sel_hi:[1,0]
	v_pk_mul_f32 v[12:13], v[12:13], v[132:133] op_sel_hi:[1,0]
	v_pk_mul_f32 v[14:15], v[14:15], v[132:133] op_sel_hi:[1,0]
	v_pk_mul_f32 v[8:9], v[8:9], v[132:133] op_sel_hi:[1,0]
	v_pk_mul_f32 v[10:11], v[10:11], v[132:133] op_sel_hi:[1,0]
	v_pk_mul_f32 v[4:5], v[4:5], v[132:133] op_sel_hi:[1,0]
	v_pk_mul_f32 v[6:7], v[6:7], v[132:133] op_sel_hi:[1,0]
	v_pk_mul_f32 v[234:235], v[16:17], s[74:75]
	v_pk_mul_f32 v[236:237], v[18:19], s[74:75]
	v_pk_mul_f32 v[238:239], v[12:13], s[74:75]
	v_pk_mul_f32 v[240:241], v[14:15], s[74:75]
	v_exp_f32_e32 v234, v234
	v_exp_f32_e32 v235, v235
	v_exp_f32_e32 v236, v236
	v_exp_f32_e32 v237, v237
	v_exp_f32_e32 v238, v238
	v_exp_f32_e32 v239, v239
	v_exp_f32_e32 v240, v240
	v_exp_f32_e32 v241, v241
	s_nop 0
	v_pk_add_f32 v[234:235], v[234:235], s[80:81]
	v_pk_add_f32 v[236:237], v[236:237], s[80:81]
	v_pk_add_f32 v[238:239], v[238:239], s[80:81]
	v_pk_add_f32 v[240:241], v[240:241], s[80:81]
	v_rcp_f32_e32 v234, v234
	v_rcp_f32_e32 v235, v235
	v_rcp_f32_e32 v236, v236
	v_rcp_f32_e32 v237, v237
	v_rcp_f32_e32 v238, v238
	v_rcp_f32_e32 v239, v239
	v_rcp_f32_e32 v240, v240
	v_rcp_f32_e32 v241, v241
	s_nop 0
	v_pk_mul_f32 v[16:17], v[16:17], v[234:235]
	v_pk_mul_f32 v[18:19], v[18:19], v[236:237]
	v_pk_mul_f32 v[12:13], v[12:13], v[238:239]
	v_pk_mul_f32 v[14:15], v[14:15], v[240:241]
	v_pk_mul_f32 v[16:17], v[8:9], v[16:17]
	v_pk_mul_f32 v[18:19], v[10:11], v[18:19]
	v_pk_mul_f32 v[12:13], v[4:5], v[12:13]
	v_pk_mul_f32 v[14:15], v[6:7], v[14:15]
	v_cvt_pk_bf16_f32 v246, v16, v17
	v_cvt_pk_bf16_f32 v247, v18, v19
	v_cvt_pk_bf16_f32 v248, v12, v13
	v_cvt_pk_bf16_f32 v249, v14, v15
	global_store_dwordx4 v[244:245], v[246:249], off
	s_andn2_b64 vcc, exec, s[42:43]
	s_mov_b64 s[4:5], -1
	s_cbranch_vccnz .LBB0_859
	s_andn2_b64 vcc, exec, s[6:7]
	s_cbranch_vccnz .LBB0_858
	s_barrier
	s_branch .LBB0_858
